# v35 + DYN publish steal chain: removed the full vmcnt(0) drain ahead of the first cross-XCD steal atomic (waitcnt placement)
# baseline (speedup 1.0000x reference)
; #define PG8_STAGE(bufoff, gbase, voff) do { _Pragma("unroll") for (int _i = 0; _i < 2; ++_i) \
;         __builtin_amdgcn_global_load_lds((const unsigned*)((const char*)(gbase) + (voff)[_i]), (LAS unsigned*)(lds + (bufoff) + ldsw + _i * 8192), 16, 0, 0); } while (0)
; #define PG8_LDA(dst, b, h) do { _Pragma("unroll") for (int m = 0; m < 4; ++m) _Pragma("unroll") for (int k = 0; k < 2; ++k) dst[m][k] = *(const LAS bf16x8*)(lds + PG8_SA(b, h) + aoff + m * 2048 + k * 1024); } while (0)
; #define PG8_LDB(dst, b, h) do { _Pragma("unroll") for (int n = 0; n < 2; ++n) _Pragma("unroll") for (int k = 0; k < 2; ++k) dst[n][k] = *(const LAS bf16x8*)(lds + PG8_SB(b, h) + boff + n * 2048 + k * 1024); } while (0)
; #define PG8_WAIT_V(n) asm volatile("s_waitcnt vmcnt(" #n ")" ::: "memory")
; template <class Epi, bool DYN = false>
; __device__ __forceinline__ void gemm_phase(LAS unsigned char* lds, const Gemm g, const Epi& E, int wave, unsigned* ctr = nullptr) {
;     ...
;             const bool last = (t == nt - 2);
;             if (DYN && last) { const int nw = __builtin_amdgcn_readfirstlane(slot[(ui + 1) & 1]); has_next = nw >= 0;
;                 if (has_next) { decode(nw, nxt); nA = (const char*)g.A + (size_t)nxt.pm * tstepA; nB = (const char*)g.Bt + (size_t)nxt.pn * tstepB; } }
;             const char* a1 = cA + (size_t)(t + 1) * kstepA;
;             const char* a2 = last ? nA : cA + (size_t)(t + 2) * kstepA; const char* b2 = last ? nB : cB + (size_t)(t + 2) * kstepB;
;             const char* a3 = a2 + kstepA; const char* b3 = b2 + kstepB;
;             PG8_LDB(B0, 0, 0); PG8_SCHED; PG8_LDA(At, 0, 0); PG8_STAGE(PG8_SA(1, 1), a1 + hstepA, voffA);
;             PG8_WAIT_L(8); PG8_BAR; PG8_WAIT_L(0); PG8_MMA(0, 0, At, B0); PG8_BAR; PG8_SCHED;
;             PG8_LDB(B1, 0, 1); PG8_STAGE(PG8_SB(0, 0), b2, voffB);
;             PG8_BAR; PG8_WAIT_L(0); PG8_MMA(0, 1, At, B1); PG8_BAR;
;             PG8_LDA(At, 0, 1); PG8_STAGE(PG8_SA(0, 0), a2, voffA);
;             PG8_BAR; PG8_WAIT_L(0); PG8_MMA(1, 0, At, B0); PG8_BAR; PG8_SCHED;
;             PG8_STAGE(PG8_SB(0, 1), b2 + hstepB, voffB);
;             PG8_WAIT_V(6); PG8_BAR; PG8_MMA(1, 1, At, B1); PG8_BAR;
;             PG8_LDB(B0, 1, 0); PG8_SCHED; PG8_LDA(At, 1, 0); PG8_STAGE(PG8_SA(0, 1), a2 + hstepA, voffA);
;             PG8_WAIT_L(8); PG8_BAR; PG8_WAIT_L(0); PG8_MMA(0, 0, At, B0); PG8_BAR; PG8_SCHED;
.LBB0_86:
	s_add_i32 s8, s8, 2
	s_add_u32 s9, s68, s72
	s_addc_u32 s10, s69, s73
	s_and_b64 s[0:1], s[38:39], exec
	s_cselect_b32 s75, s79, s10
	s_cselect_b32 s74, s78, s9
	s_add_i32 s9, 0, 0x10000
	v_add_u32_e32 v142, s9, v200
	ds_read_b128 v[130:133], v142
	ds_read_b128 v[134:137], v142 offset:1024
	ds_read_b128 v[138:141], v142 offset:2048
	ds_read_b128 v[142:145], v142 offset:3072
	s_and_b64 s[0:1], s[38:39], exec
	s_cselect_b32 s71, s65, s7
	s_cselect_b32 s70, s64, s6
	v_lshl_add_u64 v[196:197], s[68:69], 0, v[188:189]
	s_add_i32 m0, s18, 0xc000
	ds_read_b128 v[146:149], v202
	ds_read_b128 v[150:153], v202 offset:1024
	ds_read_b128 v[154:157], v202 offset:2048
	ds_read_b128 v[158:161], v202 offset:3072
	ds_read_b128 v[162:165], v202 offset:4096
	ds_read_b128 v[166:169], v202 offset:5120
	ds_read_b128 v[170:173], v202 offset:6144
	ds_read_b128 v[174:177], v202 offset:7168
	global_load_lds_dwordx4 v[196:197], off
	v_lshl_add_u64 v[196:197], s[68:69], 0, v[190:191]
	s_add_i32 m0, s18, 0xe000
	s_nop 0
	global_load_lds_dwordx4 v[196:197], off
	s_waitcnt lgkmcnt(8)
	s_barrier
	s_waitcnt lgkmcnt(0)
	s_setprio 1
	s_waitcnt lgkmcnt(0)
	v_mfma_f32_16x16x32_bf16 v[126:129], v[130:133], v[146:149], v[126:129]
	v_mfma_f32_16x16x32_bf16 v[122:125], v[138:141], v[146:149], v[122:125]
	v_mfma_f32_16x16x32_bf16 v[118:121], v[130:133], v[154:157], v[118:121]
	v_mfma_f32_16x16x32_bf16 v[114:117], v[138:141], v[154:157], v[114:117]
	v_mfma_f32_16x16x32_bf16 v[110:113], v[130:133], v[162:165], v[110:113]
	v_mfma_f32_16x16x32_bf16 v[106:109], v[138:141], v[162:165], v[106:109]
	v_mfma_f32_16x16x32_bf16 v[102:105], v[130:133], v[170:173], v[102:105]
	v_mfma_f32_16x16x32_bf16 v[94:97], v[138:141], v[170:173], v[94:97]
	v_mfma_f32_16x16x32_bf16 v[126:129], v[134:137], v[150:153], v[126:129]
	v_mfma_f32_16x16x32_bf16 v[122:125], v[142:145], v[150:153], v[122:125]
	v_mfma_f32_16x16x32_bf16 v[118:121], v[134:137], v[158:161], v[118:121]
	v_mfma_f32_16x16x32_bf16 v[114:117], v[142:145], v[158:161], v[114:117]
	v_mfma_f32_16x16x32_bf16 v[110:113], v[134:137], v[166:169], v[110:113]
	v_mfma_f32_16x16x32_bf16 v[106:109], v[142:145], v[166:169], v[106:109]
	v_mfma_f32_16x16x32_bf16 v[102:105], v[134:137], v[174:177], v[102:105]
	v_mfma_f32_16x16x32_bf16 v[94:97], v[142:145], v[174:177], v[94:97]
	s_setprio 0
	s_barrier
	s_add_i32 s10, 0, 0x14000
	s_add_i32 s0, s9, s17
	v_add_u32_e32 v212, s10, v200
	v_lshl_add_u64 v[216:217], s[70:71], 0, v[178:179]
	s_mov_b32 m0, s0
	ds_read_b128 v[196:199], v212
	ds_read_b128 v[204:207], v212 offset:1024
	ds_read_b128 v[208:211], v212 offset:2048
	ds_read_b128 v[212:215], v212 offset:3072
	global_load_lds_dwordx4 v[216:217], off
	v_lshl_add_u64 v[216:217], s[70:71], 0, v[182:183]
	s_add_i32 m0, s0, 0x2000
	s_nop 0
	global_load_lds_dwordx4 v[216:217], off
	s_barrier
	s_waitcnt lgkmcnt(0)
	s_setprio 1
	s_waitcnt lgkmcnt(0)
	v_mfma_f32_16x16x32_bf16 v[86:89], v[196:199], v[146:149], v[86:89]
	v_mfma_f32_16x16x32_bf16 v[78:81], v[208:211], v[146:149], v[78:81]
	v_mfma_f32_16x16x32_bf16 v[70:73], v[196:199], v[154:157], v[70:73]
	v_mfma_f32_16x16x32_bf16 v[62:65], v[208:211], v[154:157], v[62:65]
	v_mfma_f32_16x16x32_bf16 v[54:57], v[196:199], v[162:165], v[54:57]
	v_mfma_f32_16x16x32_bf16 v[46:49], v[208:211], v[162:165], v[46:49]
	v_mfma_f32_16x16x32_bf16 v[42:45], v[196:199], v[170:173], v[42:45]
	v_mfma_f32_16x16x32_bf16 v[38:41], v[208:211], v[170:173], v[38:41]
	v_mfma_f32_16x16x32_bf16 v[86:89], v[204:207], v[150:153], v[86:89]
	v_mfma_f32_16x16x32_bf16 v[78:81], v[212:215], v[150:153], v[78:81]
	v_mfma_f32_16x16x32_bf16 v[70:73], v[204:207], v[158:161], v[70:73]
	v_mfma_f32_16x16x32_bf16 v[62:65], v[212:215], v[158:161], v[62:65]
	v_mfma_f32_16x16x32_bf16 v[54:57], v[204:207], v[166:169], v[54:57]
	v_mfma_f32_16x16x32_bf16 v[46:49], v[212:215], v[166:169], v[46:49]
	v_mfma_f32_16x16x32_bf16 v[42:45], v[204:207], v[174:177], v[42:45]
	v_mfma_f32_16x16x32_bf16 v[38:41], v[212:215], v[174:177], v[38:41]
	s_setprio 0
	s_mov_b32 m0, s18
	v_lshl_add_u64 v[216:217], s[74:75], 0, v[0:1]
	s_barrier
	ds_read_b128 v[146:149], v202 offset:16384
	ds_read_b128 v[150:153], v202 offset:17408
	ds_read_b128 v[154:157], v202 offset:18432
	ds_read_b128 v[158:161], v202 offset:19456
	ds_read_b128 v[162:165], v202 offset:20480
	ds_read_b128 v[166:169], v202 offset:21504
	ds_read_b128 v[170:173], v202 offset:22528
	ds_read_b128 v[174:177], v202 offset:23552
	global_load_lds_dwordx4 v[216:217], off
	v_lshl_add_u64 v[218:219], s[74:75], 0, v[180:181]
	s_mov_b32 m0, s19
	s_nop 0
	global_load_lds_dwordx4 v[218:219], off
	s_barrier
	s_waitcnt lgkmcnt(0)
	s_setprio 1
	s_waitcnt lgkmcnt(0)
	v_mfma_f32_16x16x32_bf16 v[34:37], v[130:133], v[146:149], v[34:37]
	v_mfma_f32_16x16x32_bf16 v[26:29], v[138:141], v[146:149], v[26:29]
	v_mfma_f32_16x16x32_bf16 v[22:25], v[130:133], v[154:157], v[22:25]
	v_mfma_f32_16x16x32_bf16 v[18:21], v[138:141], v[154:157], v[18:21]
	v_mfma_f32_16x16x32_bf16 v[14:17], v[130:133], v[162:165], v[14:17]
	v_mfma_f32_16x16x32_bf16 v[10:13], v[138:141], v[162:165], v[10:13]
	v_mfma_f32_16x16x32_bf16 v[6:9], v[130:133], v[170:173], v[6:9]
	v_mfma_f32_16x16x32_bf16 v[2:5], v[138:141], v[170:173], v[2:5]
	v_mfma_f32_16x16x32_bf16 v[34:37], v[134:137], v[150:153], v[34:37]
	v_mfma_f32_16x16x32_bf16 v[26:29], v[142:145], v[150:153], v[26:29]
	v_mfma_f32_16x16x32_bf16 v[22:25], v[134:137], v[158:161], v[22:25]
	v_mfma_f32_16x16x32_bf16 v[18:21], v[142:145], v[158:161], v[18:21]
	v_mfma_f32_16x16x32_bf16 v[14:17], v[134:137], v[166:169], v[14:17]
	v_mfma_f32_16x16x32_bf16 v[10:13], v[142:145], v[166:169], v[10:13]
	v_mfma_f32_16x16x32_bf16 v[6:9], v[134:137], v[174:177], v[6:9]
	v_mfma_f32_16x16x32_bf16 v[2:5], v[142:145], v[174:177], v[2:5]
	s_setprio 0
	s_barrier
; #define PG8_STAGE(bufoff, gbase, voff) do { _Pragma("unroll") for (int _i = 0; _i < 2; ++_i) \
;         __builtin_amdgcn_global_load_lds((const unsigned*)((const char*)(gbase) + (voff)[_i]), (LAS unsigned*)(lds + (bufoff) + ldsw + _i * 8192), 16, 0, 0); } while (0)
; #define PG8_LDA(dst, b, h) do { _Pragma("unroll") for (int m = 0; m < 4; ++m) _Pragma("unroll") for (int k = 0; k < 2; ++k) dst[m][k] = *(const LAS bf16x8*)(lds + PG8_SA(b, h) + aoff + m * 2048 + k * 1024); } while (0)
; #define PG8_LDB(dst, b, h) do { _Pragma("unroll") for (int n = 0; n < 2; ++n) _Pragma("unroll") for (int k = 0; k < 2; ++k) dst[n][k] = *(const LAS bf16x8*)(lds + PG8_SB(b, h) + boff + n * 2048 + k * 1024); } while (0)
; #define PG8_MMA(ai, bj, At, Bt) do { __builtin_amdgcn_s_setprio(1); _Pragma("unroll") for (int m = 0; m < 4; ++m) _Pragma("unroll") for (int n = 0; n < 2; ++n) _Pragma("unroll") for (int k = 0; k < 2; ++k) \
;         acc[ai][bj][m][n] = __builtin_amdgcn_mfma_f32_16x16x32_bf16(Bt[n][k], At[m][k], acc[ai][bj][m][n], 0, 0, 0); __builtin_amdgcn_s_setprio(0); } while (0)
; #define PG8_WAIT_V(n) asm volatile("s_waitcnt vmcnt(" #n ")" ::: "memory")
; #define PG8_WAIT_L(n) asm volatile("s_waitcnt lgkmcnt(" #n ")" ::: "memory")
; #define PG8_BAR __builtin_amdgcn_s_barrier()
; #define PG8_SCHED __builtin_amdgcn_sched_barrier(0)
; template <class Epi, bool DYN = false>
; __device__ __forceinline__ void gemm_phase(LAS unsigned char* lds, const Gemm g, const Epi& E, int wave, unsigned* ctr = nullptr) {
;     ...
;             PG8_LDA(At, 0, 1); PG8_STAGE(PG8_SA(0, 0), a2, voffA);
;             PG8_BAR; PG8_WAIT_L(0); PG8_MMA(1, 0, At, B0); PG8_BAR; PG8_SCHED;
;             PG8_STAGE(PG8_SB(0, 1), b2 + hstepB, voffB);
;             PG8_WAIT_V(6); PG8_BAR; PG8_MMA(1, 1, At, B1); PG8_BAR;
;             PG8_LDB(B0, 1, 0); PG8_SCHED; PG8_LDA(At, 1, 0); PG8_STAGE(PG8_SA(0, 1), a2 + hstepA, voffA);
;             PG8_WAIT_L(8); PG8_BAR; PG8_WAIT_L(0); PG8_MMA(0, 0, At, B0); PG8_BAR; PG8_SCHED;
;             PG8_LDB(B1, 1, 1); PG8_STAGE(PG8_SB(1, 0), b3, voffB);
;             PG8_BAR; PG8_WAIT_L(0); PG8_MMA(0, 1, At, B1); PG8_BAR;
;             PG8_LDA(At, 1, 1); PG8_STAGE(PG8_SA(1, 0), a3, voffA);
;             PG8_BAR; PG8_WAIT_L(0); PG8_MMA(1, 0, At, B0); PG8_BAR; PG8_SCHED;
	s_add_u32 s0, s70, 0x4000
	s_addc_u32 s1, s71, 0
	s_add_i32 s9, s10, s17
	v_lshl_add_u64 v[130:131], s[0:1], 0, v[178:179]
	s_mov_b32 m0, s9
	s_nop 0
	global_load_lds_dwordx4 v[130:131], off
	v_lshl_add_u64 v[130:131], s[0:1], 0, v[182:183]
	s_add_i32 m0, s9, 0x2000
	s_nop 0
	global_load_lds_dwordx4 v[130:131], off
	s_waitcnt vmcnt(6)
	s_barrier
	s_setprio 1
	v_mfma_f32_16x16x32_bf16 v[98:101], v[196:199], v[146:149], v[98:101]
	v_mfma_f32_16x16x32_bf16 v[90:93], v[208:211], v[146:149], v[90:93]
	v_mfma_f32_16x16x32_bf16 v[82:85], v[196:199], v[154:157], v[82:85]
	v_mfma_f32_16x16x32_bf16 v[74:77], v[208:211], v[154:157], v[74:77]
	v_mfma_f32_16x16x32_bf16 v[66:69], v[196:199], v[162:165], v[66:69]
	v_mfma_f32_16x16x32_bf16 v[58:61], v[208:211], v[162:165], v[58:61]
	v_mfma_f32_16x16x32_bf16 v[50:53], v[196:199], v[170:173], v[50:53]
	v_mfma_f32_16x16x32_bf16 v[30:33], v[208:211], v[170:173], v[30:33]
	v_mfma_f32_16x16x32_bf16 v[98:101], v[204:207], v[150:153], v[98:101]
	v_mfma_f32_16x16x32_bf16 v[90:93], v[212:215], v[150:153], v[90:93]
	v_mfma_f32_16x16x32_bf16 v[82:85], v[204:207], v[158:161], v[82:85]
	v_mfma_f32_16x16x32_bf16 v[74:77], v[212:215], v[158:161], v[74:77]
	v_mfma_f32_16x16x32_bf16 v[66:69], v[204:207], v[166:169], v[66:69]
	v_mfma_f32_16x16x32_bf16 v[58:61], v[212:215], v[166:169], v[58:61]
	v_mfma_f32_16x16x32_bf16 v[50:53], v[204:207], v[174:177], v[50:53]
	v_mfma_f32_16x16x32_bf16 v[30:33], v[212:215], v[174:177], v[30:33]
	s_setprio 0
	s_add_i32 s9, 0, 0x18000
	v_add_u32_e32 v130, s9, v200
	s_barrier
	ds_read_b128 v[196:199], v130
	ds_read_b128 v[204:207], v130 offset:1024
	ds_read_b128 v[208:211], v130 offset:2048
	ds_read_b128 v[212:215], v130 offset:3072
	s_add_u32 s0, s74, 0x80000
	s_addc_u32 s1, s75, 0
	s_mov_b32 m0, s28
	v_lshl_add_u64 v[130:131], s[0:1], 0, v[0:1]
	ds_read_b128 v[146:149], v202 offset:32768
	ds_read_b128 v[150:153], v202 offset:33792
	ds_read_b128 v[154:157], v202 offset:34816
	ds_read_b128 v[158:161], v202 offset:35840
	ds_read_b128 v[162:165], v202 offset:36864
	ds_read_b128 v[166:169], v202 offset:37888
	ds_read_b128 v[170:173], v202 offset:38912
	ds_read_b128 v[174:177], v202 offset:39936
	global_load_lds_dwordx4 v[130:131], off
	v_lshl_add_u64 v[130:131], s[0:1], 0, v[180:181]
	s_mov_b32 m0, s33
	s_nop 0
	global_load_lds_dwordx4 v[130:131], off
	s_waitcnt lgkmcnt(8)
	s_barrier
	s_waitcnt lgkmcnt(0)
	s_setprio 1
	s_waitcnt lgkmcnt(0)
	v_mfma_f32_16x16x32_bf16 v[126:129], v[196:199], v[146:149], v[126:129]
	v_mfma_f32_16x16x32_bf16 v[122:125], v[208:211], v[146:149], v[122:125]
	v_mfma_f32_16x16x32_bf16 v[118:121], v[196:199], v[154:157], v[118:121]
	v_mfma_f32_16x16x32_bf16 v[114:117], v[208:211], v[154:157], v[114:117]
	v_mfma_f32_16x16x32_bf16 v[110:113], v[196:199], v[162:165], v[110:113]
	v_mfma_f32_16x16x32_bf16 v[106:109], v[208:211], v[162:165], v[106:109]
	v_mfma_f32_16x16x32_bf16 v[102:105], v[196:199], v[170:173], v[102:105]
	v_mfma_f32_16x16x32_bf16 v[94:97], v[208:211], v[170:173], v[94:97]
	v_mfma_f32_16x16x32_bf16 v[126:129], v[204:207], v[150:153], v[126:129]
	v_mfma_f32_16x16x32_bf16 v[122:125], v[212:215], v[150:153], v[122:125]
	v_mfma_f32_16x16x32_bf16 v[118:121], v[204:207], v[158:161], v[118:121]
	v_mfma_f32_16x16x32_bf16 v[114:117], v[212:215], v[158:161], v[114:117]
	v_mfma_f32_16x16x32_bf16 v[110:113], v[204:207], v[166:169], v[110:113]
	v_mfma_f32_16x16x32_bf16 v[106:109], v[212:215], v[166:169], v[106:109]
	v_mfma_f32_16x16x32_bf16 v[102:105], v[204:207], v[174:177], v[102:105]
	v_mfma_f32_16x16x32_bf16 v[94:97], v[212:215], v[174:177], v[94:97]
	s_setprio 0
	s_barrier
	s_add_u32 s0, s70, 0x8000
	v_add_u32_e32 v130, 0, v200
	s_addc_u32 s1, s71, 0
	s_add_i32 s9, s9, s17
	v_add_u32_e32 v142, 0x1c000, v130
	v_lshl_add_u64 v[220:221], s[0:1], 0, v[178:179]
	s_mov_b32 m0, s9
	ds_read_b128 v[130:133], v142
	ds_read_b128 v[134:137], v142 offset:1024
	ds_read_b128 v[138:141], v142 offset:2048
	ds_read_b128 v[142:145], v142 offset:3072
	global_load_lds_dwordx4 v[220:221], off
	v_lshl_add_u64 v[220:221], s[0:1], 0, v[182:183]
	s_add_i32 m0, s9, 0x2000
	s_nop 0
	global_load_lds_dwordx4 v[220:221], off
	s_barrier
; #define PG8_STAGE(bufoff, gbase, voff) do { _Pragma("unroll") for (int _i = 0; _i < 2; ++_i) \
;         __builtin_amdgcn_global_load_lds((const unsigned*)((const char*)(gbase) + (voff)[_i]), (LAS unsigned*)(lds + (bufoff) + ldsw + _i * 8192), 16, 0, 0); } while (0)
; #define PG8_LDA(dst, b, h) do { _Pragma("unroll") for (int m = 0; m < 4; ++m) _Pragma("unroll") for (int k = 0; k < 2; ++k) dst[m][k] = *(const LAS bf16x8*)(lds + PG8_SA(b, h) + aoff + m * 2048 + k * 1024); } while (0)
; #define PG8_MMA(ai, bj, At, Bt) do { __builtin_amdgcn_s_setprio(1); _Pragma("unroll") for (int m = 0; m < 4; ++m) _Pragma("unroll") for (int n = 0; n < 2; ++n) _Pragma("unroll") for (int k = 0; k < 2; ++k) \
;         acc[ai][bj][m][n] = __builtin_amdgcn_mfma_f32_16x16x32_bf16(Bt[n][k], At[m][k], acc[ai][bj][m][n], 0, 0, 0); __builtin_amdgcn_s_setprio(0); } while (0)
; #define PG8_WAIT_V(n) asm volatile("s_waitcnt vmcnt(" #n ")" ::: "memory")
; #define PG8_WAIT_L(n) asm volatile("s_waitcnt lgkmcnt(" #n ")" ::: "memory")
; #define PG8_BAR __builtin_amdgcn_s_barrier()
; #define PG8_SCHED __builtin_amdgcn_sched_barrier(0)
; template <class Epi, bool DYN = false>
; __device__ __forceinline__ void gemm_phase(LAS unsigned char* lds, const Gemm g, const Epi& E, int wave, unsigned* ctr = nullptr) {
;     ...
;     auto publish = [&](int si) { if (tid == 0) { int wg = -1;
;             if (ticket < rng_cnt(xcd)) wg = rng_start(xcd) + ticket;
;             else { for (int k = 1; k < 8; ++k) { const int x2 = (xcd + k) & 7; const int t2 = (int)__hip_atomic_fetch_add(ctr + x2 * 16, 1u, __ATOMIC_RELAXED, __HIP_MEMORY_SCOPE_AGENT); if (t2 < rng_cnt(x2)) { wg = rng_start(x2) + t2; break; } } }
;             slot[si] = wg; } };
;     ...
;             PG8_BAR; PG8_WAIT_L(0); PG8_MMA(0, 1, At, B1); PG8_BAR;
;             PG8_LDA(At, 1, 1); PG8_STAGE(PG8_SA(1, 0), a3, voffA);
;             PG8_BAR; PG8_WAIT_L(0); PG8_MMA(1, 0, At, B0); PG8_BAR; PG8_SCHED;
;             if (DYN && t == 0) publish((ui + 1) & 1);
;             PG8_STAGE(PG8_SB(1, 1), b3 + hstepB, voffB);
;             PG8_WAIT_V(6); PG8_BAR; PG8_MMA(1, 1, At, B1); PG8_BAR;
	s_waitcnt lgkmcnt(0)
	s_setprio 1
	s_waitcnt lgkmcnt(0)
	v_mfma_f32_16x16x32_bf16 v[86:89], v[130:133], v[146:149], v[86:89]
	v_mfma_f32_16x16x32_bf16 v[78:81], v[138:141], v[146:149], v[78:81]
	v_mfma_f32_16x16x32_bf16 v[70:73], v[130:133], v[154:157], v[70:73]
	v_mfma_f32_16x16x32_bf16 v[62:65], v[138:141], v[154:157], v[62:65]
	v_mfma_f32_16x16x32_bf16 v[54:57], v[130:133], v[162:165], v[54:57]
	v_mfma_f32_16x16x32_bf16 v[46:49], v[138:141], v[162:165], v[46:49]
	v_mfma_f32_16x16x32_bf16 v[42:45], v[130:133], v[170:173], v[42:45]
	v_mfma_f32_16x16x32_bf16 v[38:41], v[138:141], v[170:173], v[38:41]
	v_mfma_f32_16x16x32_bf16 v[86:89], v[134:137], v[150:153], v[86:89]
	v_mfma_f32_16x16x32_bf16 v[78:81], v[142:145], v[150:153], v[78:81]
	v_mfma_f32_16x16x32_bf16 v[70:73], v[134:137], v[158:161], v[70:73]
	v_mfma_f32_16x16x32_bf16 v[62:65], v[142:145], v[158:161], v[62:65]
	v_mfma_f32_16x16x32_bf16 v[54:57], v[134:137], v[166:169], v[54:57]
	v_mfma_f32_16x16x32_bf16 v[46:49], v[142:145], v[166:169], v[46:49]
	v_mfma_f32_16x16x32_bf16 v[42:45], v[134:137], v[174:177], v[42:45]
	v_mfma_f32_16x16x32_bf16 v[38:41], v[142:145], v[174:177], v[38:41]
	s_setprio 0
	s_mov_b32 m0, s41
	v_lshl_add_u64 v[216:217], v[216:217], 0, s[52:53]
	s_barrier
	ds_read_b128 v[170:173], v202 offset:49152
	ds_read_b128 v[174:177], v202 offset:50176
	ds_read_b128 v[162:165], v202 offset:51200
	ds_read_b128 v[166:169], v202 offset:52224
	ds_read_b128 v[154:157], v202 offset:53248
	ds_read_b128 v[158:161], v202 offset:54272
	ds_read_b128 v[146:149], v202 offset:55296
	ds_read_b128 v[150:153], v202 offset:56320
	global_load_lds_dwordx4 v[216:217], off
	v_lshl_add_u64 v[216:217], v[218:219], 0, s[52:53]
	s_mov_b32 m0, s43
	s_nop 0
	global_load_lds_dwordx4 v[216:217], off
	s_barrier
	s_waitcnt lgkmcnt(0)
	s_setprio 1
	s_waitcnt lgkmcnt(0)
	v_mfma_f32_16x16x32_bf16 v[34:37], v[196:199], v[170:173], v[34:37]
	v_mfma_f32_16x16x32_bf16 v[26:29], v[208:211], v[170:173], v[26:29]
	v_mfma_f32_16x16x32_bf16 v[22:25], v[196:199], v[162:165], v[22:25]
	v_mfma_f32_16x16x32_bf16 v[18:21], v[208:211], v[162:165], v[18:21]
	v_mfma_f32_16x16x32_bf16 v[14:17], v[196:199], v[154:157], v[14:17]
	v_mfma_f32_16x16x32_bf16 v[10:13], v[208:211], v[154:157], v[10:13]
	v_mfma_f32_16x16x32_bf16 v[6:9], v[196:199], v[146:149], v[6:9]
	v_mfma_f32_16x16x32_bf16 v[2:5], v[208:211], v[146:149], v[2:5]
	v_mfma_f32_16x16x32_bf16 v[34:37], v[204:207], v[174:177], v[34:37]
	v_mfma_f32_16x16x32_bf16 v[26:29], v[212:215], v[174:177], v[26:29]
	v_mfma_f32_16x16x32_bf16 v[22:25], v[204:207], v[166:169], v[22:25]
	v_mfma_f32_16x16x32_bf16 v[18:21], v[212:215], v[166:169], v[18:21]
	v_mfma_f32_16x16x32_bf16 v[14:17], v[204:207], v[158:161], v[14:17]
	v_mfma_f32_16x16x32_bf16 v[10:13], v[212:215], v[158:161], v[10:13]
	v_mfma_f32_16x16x32_bf16 v[6:9], v[204:207], v[150:153], v[6:9]
	v_mfma_f32_16x16x32_bf16 v[2:5], v[212:215], v[150:153], v[2:5]
	s_setprio 0
	s_barrier
	v_or_b32_e32 v196, s8, v192
	v_cmp_eq_u32_e64 s[38:39], 0, v196
	s_and_saveexec_b64 s[74:75], s[38:39]
	s_cbranch_execz .LBB0_81
	v_cmp_lt_i32_e32 vcc, s91, v193
	v_add_u32_e32 v203, s23, v193
	v_mov_b32_e32 v204, v203
	s_and_saveexec_b64 s[36:37], vcc
	s_cbranch_execz .LBB0_80
	v_mov_b64_e32 v[196:197], s[44:45]
	flat_atomic_add v196, v[196:197], v224 sc0
	s_waitcnt vmcnt(0) lgkmcnt(0)
	v_cmp_lt_i32_e64 s[38:39], s91, v196
	v_add_u32_e32 v204, s2, v196
	s_and_saveexec_b64 s[0:1], s[38:39]
	s_cbranch_execz .LBB0_79
	v_mov_b64_e32 v[196:197], s[58:59]
	flat_atomic_add v196, v[196:197], v224 sc0
	s_waitcnt vmcnt(0) lgkmcnt(0)
	v_cmp_lt_i32_e64 s[38:39], s91, v196
	v_add_u32_e32 v204, s66, v196
	s_and_saveexec_b64 s[80:81], s[38:39]
	s_cbranch_execz .LBB0_78
	v_mov_b64_e32 v[196:197], s[60:61]
	flat_atomic_add v196, v[196:197], v224 sc0
	s_movk_i32 s9, 0x60
	s_waitcnt vmcnt(0) lgkmcnt(0)
	v_cmp_lt_i32_e64 s[38:39], s91, v196
	v_add_u32_e32 v204, s67, v196
	s_and_saveexec_b64 s[82:83], s[38:39]
	s_cbranch_execz .LBB0_77
	v_mov_b64_e32 v[196:197], s[62:63]
	flat_atomic_add v196, v[196:197], v224 sc0
	s_waitcnt vmcnt(0) lgkmcnt(0)
	v_cmp_lt_i32_e64 s[38:39], s91, v196
	v_add_u32_e32 v204, s22, v196
	s_and_saveexec_b64 s[84:85], s[38:39]
	s_cbranch_execz .LBB0_76
	v_mov_b64_e32 v[196:197], s[92:93]
	flat_atomic_add v196, v[196:197], v224 sc0
	v_readlane_b32 s10, v255, 2
	s_waitcnt vmcnt(0) lgkmcnt(0)
	v_cmp_lt_i32_e64 s[38:39], s91, v196
	v_add_u32_e32 v204, s10, v196
	s_and_saveexec_b64 s[86:87], s[38:39]
	s_cbranch_execz .LBB0_75
	v_readlane_b32 s38, v255, 4
	v_readlane_b32 s39, v255, 5
	v_readlane_b32 s10, v255, 6
	s_nop 0
	v_mov_b64_e32 v[196:197], s[38:39]
	flat_atomic_add v196, v[196:197], v224 sc0
	s_waitcnt vmcnt(0) lgkmcnt(0)
	v_cmp_lt_i32_e64 s[38:39], s91, v196
	v_add_u32_e32 v204, s10, v196
	s_and_saveexec_b64 s[88:89], s[38:39]
	s_cbranch_execz .LBB0_74
	v_readlane_b32 s38, v255, 8
	v_readlane_b32 s39, v255, 9
	v_readlane_b32 s10, v255, 10
	s_nop 0
	v_mov_b64_e32 v[196:197], s[38:39]
	flat_atomic_add v196, v[196:197], v224 sc0
	s_waitcnt vmcnt(0) lgkmcnt(0)
	v_add_u32_e32 v197, s10, v196
	v_cmp_gt_i32_e64 s[38:39], s9, v196
	s_nop 1
	v_cndmask_b32_e64 v204, -1, v197, s[38:39]
	s_branch .LBB0_74

; #define PG8_STAGE(bufoff, gbase, voff) do { _Pragma("unroll") for (int _i = 0; _i < 2; ++_i) \
;         __builtin_amdgcn_global_load_lds((const unsigned*)((const char*)(gbase) + (voff)[_i]), (LAS unsigned*)(lds + (bufoff) + ldsw + _i * 8192), 16, 0, 0); } while (0)
; #define PG8_LDA(dst, b, h) do { _Pragma("unroll") for (int m = 0; m < 4; ++m) _Pragma("unroll") for (int k = 0; k < 2; ++k) dst[m][k] = *(const LAS bf16x8*)(lds + PG8_SA(b, h) + aoff + m * 2048 + k * 1024); } while (0)
; #define PG8_LDB(dst, b, h) do { _Pragma("unroll") for (int n = 0; n < 2; ++n) _Pragma("unroll") for (int k = 0; k < 2; ++k) dst[n][k] = *(const LAS bf16x8*)(lds + PG8_SB(b, h) + boff + n * 2048 + k * 1024); } while (0)
; #define PG8_WAIT_V(n) asm volatile("s_waitcnt vmcnt(" #n ")" ::: "memory")
; template <class Epi, bool DYN = false>
; __device__ __forceinline__ void gemm_phase(LAS unsigned char* lds, const Gemm g, const Epi& E, int wave, unsigned* ctr = nullptr) {
;     ...
;             const bool last = (t == nt - 2);
;             if (DYN && last) { const int nw = __builtin_amdgcn_readfirstlane(slot[(ui + 1) & 1]); has_next = nw >= 0;
;                 if (has_next) { decode(nw, nxt); nA = (const char*)g.A + (size_t)nxt.pm * tstepA; nB = (const char*)g.Bt + (size_t)nxt.pn * tstepB; } }
;             const char* a1 = cA + (size_t)(t + 1) * kstepA;
;             const char* a2 = last ? nA : cA + (size_t)(t + 2) * kstepA; const char* b2 = last ? nB : cB + (size_t)(t + 2) * kstepB;
;             const char* a3 = a2 + kstepA; const char* b3 = b2 + kstepB;
;             PG8_LDB(B0, 0, 0); PG8_SCHED; PG8_LDA(At, 0, 0); PG8_STAGE(PG8_SA(1, 1), a1 + hstepA, voffA);
;             PG8_WAIT_L(8); PG8_BAR; PG8_WAIT_L(0); PG8_MMA(0, 0, At, B0); PG8_BAR; PG8_SCHED;
;             PG8_LDB(B1, 0, 1); PG8_STAGE(PG8_SB(0, 0), b2, voffB);
;             PG8_BAR; PG8_WAIT_L(0); PG8_MMA(0, 1, At, B1); PG8_BAR;
;             PG8_LDA(At, 0, 1); PG8_STAGE(PG8_SA(0, 0), a2, voffA);
;             PG8_BAR; PG8_WAIT_L(0); PG8_MMA(1, 0, At, B0); PG8_BAR; PG8_SCHED;
;             PG8_STAGE(PG8_SB(0, 1), b2 + hstepB, voffB);
;             PG8_WAIT_V(6); PG8_BAR; PG8_MMA(1, 1, At, B1); PG8_BAR;
;             PG8_LDB(B0, 1, 0); PG8_SCHED; PG8_LDA(At, 1, 0); PG8_STAGE(PG8_SA(0, 1), a2 + hstepA, voffA);
;             PG8_WAIT_L(8); PG8_BAR; PG8_WAIT_L(0); PG8_MMA(0, 0, At, B0); PG8_BAR; PG8_SCHED;
.LBB0_510:
	s_add_i32 s3, s3, 2
	s_add_u32 s0, s74, s40
	s_addc_u32 s1, s75, s41
	s_add_u32 s4, s0, 0x10000
	s_addc_u32 s5, s1, 0
	s_and_b64 s[0:1], s[36:37], exec
	s_cselect_b32 s43, s77, s5
	s_cselect_b32 s42, s76, s4
	s_add_u32 s4, s19, s40
	s_addc_u32 s5, s15, s41
	s_add_u32 s38, s42, 0x8000
	s_addc_u32 s39, s43, 0
	s_add_i32 s6, 0, 0x10000
	v_add_u32_e32 v142, s6, v201
	ds_read_b128 v[130:133], v142
	ds_read_b128 v[134:137], v142 offset:1024
	ds_read_b128 v[138:141], v142 offset:2048
	ds_read_b128 v[142:145], v142 offset:3072
	s_and_b64 s[0:1], s[36:37], exec
	s_cselect_b32 s37, s67, s5
	s_cselect_b32 s36, s66, s4
	v_lshl_add_u64 v[196:197], v[210:211], 0, s[40:41]
	s_add_i32 m0, s45, 0xc000
	ds_read_b128 v[146:149], v212
	ds_read_b128 v[150:153], v212 offset:1024
	ds_read_b128 v[154:157], v212 offset:2048
	ds_read_b128 v[158:161], v212 offset:3072
	ds_read_b128 v[162:165], v212 offset:4096
	ds_read_b128 v[166:169], v212 offset:5120
	ds_read_b128 v[170:173], v212 offset:6144
	ds_read_b128 v[174:177], v212 offset:7168
	global_load_lds_dwordx4 v[196:197], off
	v_lshl_add_u64 v[196:197], v[208:209], 0, s[40:41]
	s_add_i32 m0, s45, 0xe000
	s_nop 0
	global_load_lds_dwordx4 v[196:197], off
	s_waitcnt lgkmcnt(8)
	s_barrier
	s_waitcnt lgkmcnt(0)
	s_setprio 1
	s_waitcnt lgkmcnt(0)
	v_mfma_f32_16x16x32_bf16 v[2:5], v[130:133], v[146:149], v[2:5]
	v_mfma_f32_16x16x32_bf16 v[30:33], v[138:141], v[146:149], v[30:33]
	v_mfma_f32_16x16x32_bf16 v[26:29], v[130:133], v[154:157], v[26:29]
	v_mfma_f32_16x16x32_bf16 v[22:25], v[138:141], v[154:157], v[22:25]
	v_mfma_f32_16x16x32_bf16 v[18:21], v[130:133], v[162:165], v[18:21]
	v_mfma_f32_16x16x32_bf16 v[14:17], v[138:141], v[162:165], v[14:17]
	v_mfma_f32_16x16x32_bf16 v[10:13], v[130:133], v[170:173], v[10:13]
	v_mfma_f32_16x16x32_bf16 v[6:9], v[138:141], v[170:173], v[6:9]
	v_mfma_f32_16x16x32_bf16 v[2:5], v[134:137], v[150:153], v[2:5]
	v_mfma_f32_16x16x32_bf16 v[30:33], v[142:145], v[150:153], v[30:33]
	v_mfma_f32_16x16x32_bf16 v[26:29], v[134:137], v[158:161], v[26:29]
	v_mfma_f32_16x16x32_bf16 v[22:25], v[142:145], v[158:161], v[22:25]
	v_mfma_f32_16x16x32_bf16 v[18:21], v[134:137], v[166:169], v[18:21]
	v_mfma_f32_16x16x32_bf16 v[14:17], v[142:145], v[166:169], v[14:17]
	v_mfma_f32_16x16x32_bf16 v[10:13], v[134:137], v[174:177], v[10:13]
	v_mfma_f32_16x16x32_bf16 v[6:9], v[142:145], v[174:177], v[6:9]
	s_setprio 0
	s_barrier
	s_add_i32 s4, 0, 0x14000
	s_add_i32 s0, s6, s81
	v_add_u32_e32 v232, s4, v201
	v_lshl_add_u64 v[244:245], s[36:37], 0, v[0:1]
	s_mov_b32 m0, s0
	ds_read_b128 v[196:199], v232
	ds_read_b128 v[214:217], v232 offset:1024
	ds_read_b128 v[218:221], v232 offset:2048
	ds_read_b128 v[232:235], v232 offset:3072
	global_load_lds_dwordx4 v[244:245], off
	v_lshl_add_u64 v[244:245], s[36:37], 0, v[182:183]
	s_add_i32 m0, s0, 0x2000
	s_nop 0
	global_load_lds_dwordx4 v[244:245], off
	s_barrier
	s_waitcnt lgkmcnt(0)
	s_setprio 1
	s_waitcnt lgkmcnt(0)
	v_mfma_f32_16x16x32_bf16 v[94:97], v[196:199], v[146:149], v[94:97]
	v_mfma_f32_16x16x32_bf16 v[90:93], v[218:221], v[146:149], v[90:93]
	v_mfma_f32_16x16x32_bf16 v[86:89], v[196:199], v[154:157], v[86:89]
	v_mfma_f32_16x16x32_bf16 v[82:85], v[218:221], v[154:157], v[82:85]
	v_mfma_f32_16x16x32_bf16 v[78:81], v[196:199], v[162:165], v[78:81]
	v_mfma_f32_16x16x32_bf16 v[74:77], v[218:221], v[162:165], v[74:77]
	v_mfma_f32_16x16x32_bf16 v[70:73], v[196:199], v[170:173], v[70:73]
	v_mfma_f32_16x16x32_bf16 v[66:69], v[218:221], v[170:173], v[66:69]
	v_mfma_f32_16x16x32_bf16 v[94:97], v[214:217], v[150:153], v[94:97]
	v_mfma_f32_16x16x32_bf16 v[90:93], v[232:235], v[150:153], v[90:93]
	v_mfma_f32_16x16x32_bf16 v[86:89], v[214:217], v[158:161], v[86:89]
	v_mfma_f32_16x16x32_bf16 v[82:85], v[232:235], v[158:161], v[82:85]
	v_mfma_f32_16x16x32_bf16 v[78:81], v[214:217], v[166:169], v[78:81]
	v_mfma_f32_16x16x32_bf16 v[74:77], v[232:235], v[166:169], v[74:77]
	v_mfma_f32_16x16x32_bf16 v[70:73], v[214:217], v[174:177], v[70:73]
	v_mfma_f32_16x16x32_bf16 v[66:69], v[232:235], v[174:177], v[66:69]
	s_setprio 0
	s_mov_b32 m0, s45
	v_lshl_add_u64 v[244:245], s[42:43], 0, v[178:179]
	s_barrier
	ds_read_b128 v[146:149], v212 offset:16384
	ds_read_b128 v[150:153], v212 offset:17408
	ds_read_b128 v[154:157], v212 offset:18432
	ds_read_b128 v[158:161], v212 offset:19456
	ds_read_b128 v[162:165], v212 offset:20480
	ds_read_b128 v[166:169], v212 offset:21504
	ds_read_b128 v[170:173], v212 offset:22528
	ds_read_b128 v[174:177], v212 offset:23552
	global_load_lds_dwordx4 v[244:245], off
	v_lshl_add_u64 v[244:245], s[42:43], 0, v[180:181]
	s_mov_b32 m0, s83
	s_nop 0
	global_load_lds_dwordx4 v[244:245], off
	s_barrier
	s_waitcnt lgkmcnt(0)
	s_setprio 1
	s_waitcnt lgkmcnt(0)
	v_mfma_f32_16x16x32_bf16 v[62:65], v[130:133], v[146:149], v[62:65]
	v_mfma_f32_16x16x32_bf16 v[58:61], v[138:141], v[146:149], v[58:61]
	v_mfma_f32_16x16x32_bf16 v[54:57], v[130:133], v[154:157], v[54:57]
	v_mfma_f32_16x16x32_bf16 v[50:53], v[138:141], v[154:157], v[50:53]
	v_mfma_f32_16x16x32_bf16 v[46:49], v[130:133], v[162:165], v[46:49]
	v_mfma_f32_16x16x32_bf16 v[42:45], v[138:141], v[162:165], v[42:45]
	v_mfma_f32_16x16x32_bf16 v[38:41], v[130:133], v[170:173], v[38:41]
	v_mfma_f32_16x16x32_bf16 v[34:37], v[138:141], v[170:173], v[34:37]
	v_mfma_f32_16x16x32_bf16 v[62:65], v[134:137], v[150:153], v[62:65]
	v_mfma_f32_16x16x32_bf16 v[58:61], v[142:145], v[150:153], v[58:61]
	v_mfma_f32_16x16x32_bf16 v[54:57], v[134:137], v[158:161], v[54:57]
	v_mfma_f32_16x16x32_bf16 v[50:53], v[142:145], v[158:161], v[50:53]
	v_mfma_f32_16x16x32_bf16 v[46:49], v[134:137], v[166:169], v[46:49]
	v_mfma_f32_16x16x32_bf16 v[42:45], v[142:145], v[166:169], v[42:45]
	v_mfma_f32_16x16x32_bf16 v[38:41], v[134:137], v[174:177], v[38:41]
	v_mfma_f32_16x16x32_bf16 v[34:37], v[142:145], v[174:177], v[34:37]
	s_setprio 0
	s_barrier
; #define PG8_STAGE(bufoff, gbase, voff) do { _Pragma("unroll") for (int _i = 0; _i < 2; ++_i) \
;         __builtin_amdgcn_global_load_lds((const unsigned*)((const char*)(gbase) + (voff)[_i]), (LAS unsigned*)(lds + (bufoff) + ldsw + _i * 8192), 16, 0, 0); } while (0)
; #define PG8_LDA(dst, b, h) do { _Pragma("unroll") for (int m = 0; m < 4; ++m) _Pragma("unroll") for (int k = 0; k < 2; ++k) dst[m][k] = *(const LAS bf16x8*)(lds + PG8_SA(b, h) + aoff + m * 2048 + k * 1024); } while (0)
; #define PG8_LDB(dst, b, h) do { _Pragma("unroll") for (int n = 0; n < 2; ++n) _Pragma("unroll") for (int k = 0; k < 2; ++k) dst[n][k] = *(const LAS bf16x8*)(lds + PG8_SB(b, h) + boff + n * 2048 + k * 1024); } while (0)
; #define PG8_MMA(ai, bj, At, Bt) do { __builtin_amdgcn_s_setprio(1); _Pragma("unroll") for (int m = 0; m < 4; ++m) _Pragma("unroll") for (int n = 0; n < 2; ++n) _Pragma("unroll") for (int k = 0; k < 2; ++k) \
;         acc[ai][bj][m][n] = __builtin_amdgcn_mfma_f32_16x16x32_bf16(Bt[n][k], At[m][k], acc[ai][bj][m][n], 0, 0, 0); __builtin_amdgcn_s_setprio(0); } while (0)
; #define PG8_WAIT_V(n) asm volatile("s_waitcnt vmcnt(" #n ")" ::: "memory")
; #define PG8_WAIT_L(n) asm volatile("s_waitcnt lgkmcnt(" #n ")" ::: "memory")
; #define PG8_BAR __builtin_amdgcn_s_barrier()
; #define PG8_SCHED __builtin_amdgcn_sched_barrier(0)
; template <class Epi, bool DYN = false>
; __device__ __forceinline__ void gemm_phase(LAS unsigned char* lds, const Gemm g, const Epi& E, int wave, unsigned* ctr = nullptr) {
;     ...
;             PG8_LDA(At, 0, 1); PG8_STAGE(PG8_SA(0, 0), a2, voffA);
;             PG8_BAR; PG8_WAIT_L(0); PG8_MMA(1, 0, At, B0); PG8_BAR; PG8_SCHED;
;             PG8_STAGE(PG8_SB(0, 1), b2 + hstepB, voffB);
;             PG8_WAIT_V(6); PG8_BAR; PG8_MMA(1, 1, At, B1); PG8_BAR;
;             PG8_LDB(B0, 1, 0); PG8_SCHED; PG8_LDA(At, 1, 0); PG8_STAGE(PG8_SA(0, 1), a2 + hstepA, voffA);
;             PG8_WAIT_L(8); PG8_BAR; PG8_WAIT_L(0); PG8_MMA(0, 0, At, B0); PG8_BAR; PG8_SCHED;
;             PG8_LDB(B1, 1, 1); PG8_STAGE(PG8_SB(1, 0), b3, voffB);
;             PG8_BAR; PG8_WAIT_L(0); PG8_MMA(0, 1, At, B1); PG8_BAR;
;             PG8_LDA(At, 1, 1); PG8_STAGE(PG8_SA(1, 0), a3, voffA);
;             PG8_BAR; PG8_WAIT_L(0); PG8_MMA(1, 0, At, B0); PG8_BAR; PG8_SCHED;
	s_add_u32 s0, s36, 0x4000
	s_addc_u32 s1, s37, 0
	s_add_i32 s4, s4, s81
	v_lshl_add_u64 v[130:131], s[0:1], 0, v[0:1]
	s_mov_b32 m0, s4
	s_nop 0
	global_load_lds_dwordx4 v[130:131], off
	v_lshl_add_u64 v[130:131], s[0:1], 0, v[182:183]
	s_add_i32 m0, s4, 0x2000
	s_nop 0
	global_load_lds_dwordx4 v[130:131], off
	s_waitcnt vmcnt(6)
	s_barrier
	s_setprio 1
	v_mfma_f32_16x16x32_bf16 v[126:129], v[196:199], v[146:149], v[126:129]
	v_mfma_f32_16x16x32_bf16 v[122:125], v[218:221], v[146:149], v[122:125]
	v_mfma_f32_16x16x32_bf16 v[118:121], v[196:199], v[154:157], v[118:121]
	v_mfma_f32_16x16x32_bf16 v[114:117], v[218:221], v[154:157], v[114:117]
	v_mfma_f32_16x16x32_bf16 v[110:113], v[196:199], v[162:165], v[110:113]
	v_mfma_f32_16x16x32_bf16 v[106:109], v[218:221], v[162:165], v[106:109]
	v_mfma_f32_16x16x32_bf16 v[102:105], v[196:199], v[170:173], v[102:105]
	v_mfma_f32_16x16x32_bf16 v[98:101], v[218:221], v[170:173], v[98:101]
	v_mfma_f32_16x16x32_bf16 v[126:129], v[214:217], v[150:153], v[126:129]
	v_mfma_f32_16x16x32_bf16 v[122:125], v[232:235], v[150:153], v[122:125]
	v_mfma_f32_16x16x32_bf16 v[118:121], v[214:217], v[158:161], v[118:121]
	v_mfma_f32_16x16x32_bf16 v[114:117], v[232:235], v[158:161], v[114:117]
	v_mfma_f32_16x16x32_bf16 v[110:113], v[214:217], v[166:169], v[110:113]
	v_mfma_f32_16x16x32_bf16 v[106:109], v[232:235], v[166:169], v[106:109]
	v_mfma_f32_16x16x32_bf16 v[102:105], v[214:217], v[174:177], v[102:105]
	v_mfma_f32_16x16x32_bf16 v[98:101], v[232:235], v[174:177], v[98:101]
	s_setprio 0
	s_add_i32 s4, 0, 0x18000
	v_add_u32_e32 v130, s4, v201
	s_barrier
	ds_read_b128 v[196:199], v130
	ds_read_b128 v[214:217], v130 offset:1024
	ds_read_b128 v[218:221], v130 offset:2048
	ds_read_b128 v[232:235], v130 offset:3072
	s_add_u32 s0, s42, 0x4000
	s_addc_u32 s1, s43, 0
	s_mov_b32 m0, s84
	v_lshl_add_u64 v[130:131], s[0:1], 0, v[178:179]
	ds_read_b128 v[146:149], v212 offset:32768
	ds_read_b128 v[150:153], v212 offset:33792
	ds_read_b128 v[154:157], v212 offset:34816
	ds_read_b128 v[158:161], v212 offset:35840
	ds_read_b128 v[162:165], v212 offset:36864
	ds_read_b128 v[166:169], v212 offset:37888
	ds_read_b128 v[170:173], v212 offset:38912
	ds_read_b128 v[174:177], v212 offset:39936
	global_load_lds_dwordx4 v[130:131], off
	v_lshl_add_u64 v[130:131], s[0:1], 0, v[180:181]
	s_mov_b32 m0, s85
	s_nop 0
	global_load_lds_dwordx4 v[130:131], off
	s_waitcnt lgkmcnt(8)
	s_barrier
	s_waitcnt lgkmcnt(0)
	s_setprio 1
	s_waitcnt lgkmcnt(0)
	v_mfma_f32_16x16x32_bf16 v[2:5], v[196:199], v[146:149], v[2:5]
	v_mfma_f32_16x16x32_bf16 v[30:33], v[218:221], v[146:149], v[30:33]
	v_mfma_f32_16x16x32_bf16 v[26:29], v[196:199], v[154:157], v[26:29]
	v_mfma_f32_16x16x32_bf16 v[22:25], v[218:221], v[154:157], v[22:25]
	v_mfma_f32_16x16x32_bf16 v[18:21], v[196:199], v[162:165], v[18:21]
	v_mfma_f32_16x16x32_bf16 v[14:17], v[218:221], v[162:165], v[14:17]
	v_mfma_f32_16x16x32_bf16 v[10:13], v[196:199], v[170:173], v[10:13]
	v_mfma_f32_16x16x32_bf16 v[6:9], v[218:221], v[170:173], v[6:9]
	v_mfma_f32_16x16x32_bf16 v[2:5], v[214:217], v[150:153], v[2:5]
	v_mfma_f32_16x16x32_bf16 v[30:33], v[232:235], v[150:153], v[30:33]
	v_mfma_f32_16x16x32_bf16 v[26:29], v[214:217], v[158:161], v[26:29]
	v_mfma_f32_16x16x32_bf16 v[22:25], v[232:235], v[158:161], v[22:25]
	v_mfma_f32_16x16x32_bf16 v[18:21], v[214:217], v[166:169], v[18:21]
	v_mfma_f32_16x16x32_bf16 v[14:17], v[232:235], v[166:169], v[14:17]
	v_mfma_f32_16x16x32_bf16 v[10:13], v[214:217], v[174:177], v[10:13]
	v_mfma_f32_16x16x32_bf16 v[6:9], v[232:235], v[174:177], v[6:9]
	s_setprio 0
	s_barrier
	s_add_u32 s0, s36, 0x8000
	v_add_u32_e32 v130, 0, v201
	s_addc_u32 s1, s37, 0
	s_add_i32 s4, s4, s81
	v_add_u32_e32 v142, 0x1c000, v130
	v_lshl_add_u64 v[244:245], s[0:1], 0, v[0:1]
	s_mov_b32 m0, s4
	ds_read_b128 v[130:133], v142
	ds_read_b128 v[134:137], v142 offset:1024
	ds_read_b128 v[138:141], v142 offset:2048
	ds_read_b128 v[142:145], v142 offset:3072
	global_load_lds_dwordx4 v[244:245], off
	v_lshl_add_u64 v[244:245], s[0:1], 0, v[182:183]
	s_add_i32 m0, s4, 0x2000
	s_nop 0
	global_load_lds_dwordx4 v[244:245], off
	s_barrier
	s_waitcnt lgkmcnt(0)
	s_setprio 1
	s_waitcnt lgkmcnt(0)
	v_mfma_f32_16x16x32_bf16 v[94:97], v[130:133], v[146:149], v[94:97]
	v_mfma_f32_16x16x32_bf16 v[90:93], v[138:141], v[146:149], v[90:93]
	v_mfma_f32_16x16x32_bf16 v[86:89], v[130:133], v[154:157], v[86:89]
	v_mfma_f32_16x16x32_bf16 v[82:85], v[138:141], v[154:157], v[82:85]
	v_mfma_f32_16x16x32_bf16 v[78:81], v[130:133], v[162:165], v[78:81]
	v_mfma_f32_16x16x32_bf16 v[74:77], v[138:141], v[162:165], v[74:77]
	v_mfma_f32_16x16x32_bf16 v[70:73], v[130:133], v[170:173], v[70:73]
	v_mfma_f32_16x16x32_bf16 v[66:69], v[138:141], v[170:173], v[66:69]
	v_mfma_f32_16x16x32_bf16 v[94:97], v[134:137], v[150:153], v[94:97]
	v_mfma_f32_16x16x32_bf16 v[90:93], v[142:145], v[150:153], v[90:93]
	v_mfma_f32_16x16x32_bf16 v[86:89], v[134:137], v[158:161], v[86:89]
	v_mfma_f32_16x16x32_bf16 v[82:85], v[142:145], v[158:161], v[82:85]
	v_mfma_f32_16x16x32_bf16 v[78:81], v[134:137], v[166:169], v[78:81]
	v_mfma_f32_16x16x32_bf16 v[74:77], v[142:145], v[166:169], v[74:77]
	v_mfma_f32_16x16x32_bf16 v[70:73], v[134:137], v[174:177], v[70:73]
	v_mfma_f32_16x16x32_bf16 v[66:69], v[142:145], v[174:177], v[66:69]
	s_setprio 0
	s_mov_b32 m0, s86
	v_lshl_add_u64 v[244:245], s[38:39], 0, v[178:179]
	s_barrier
; #define PG8_STAGE(bufoff, gbase, voff) do { _Pragma("unroll") for (int _i = 0; _i < 2; ++_i) \
;         __builtin_amdgcn_global_load_lds((const unsigned*)((const char*)(gbase) + (voff)[_i]), (LAS unsigned*)(lds + (bufoff) + ldsw + _i * 8192), 16, 0, 0); } while (0)
; #define PG8_LDA(dst, b, h) do { _Pragma("unroll") for (int m = 0; m < 4; ++m) _Pragma("unroll") for (int k = 0; k < 2; ++k) dst[m][k] = *(const LAS bf16x8*)(lds + PG8_SA(b, h) + aoff + m * 2048 + k * 1024); } while (0)
; #define PG8_LDB(dst, b, h) do { _Pragma("unroll") for (int n = 0; n < 2; ++n) _Pragma("unroll") for (int k = 0; k < 2; ++k) dst[n][k] = *(const LAS bf16x8*)(lds + PG8_SB(b, h) + boff + n * 2048 + k * 1024); } while (0)
; #define PG8_MMA(ai, bj, At, Bt) do { __builtin_amdgcn_s_setprio(1); _Pragma("unroll") for (int m = 0; m < 4; ++m) _Pragma("unroll") for (int n = 0; n < 2; ++n) _Pragma("unroll") for (int k = 0; k < 2; ++k) \
;         acc[ai][bj][m][n] = __builtin_amdgcn_mfma_f32_16x16x32_bf16(Bt[n][k], At[m][k], acc[ai][bj][m][n], 0, 0, 0); __builtin_amdgcn_s_setprio(0); } while (0)
; template <class Epi, bool DYN = false>
; __device__ __forceinline__ void gemm_phase(LAS unsigned char* lds, const Gemm g, const Epi& E, int wave, unsigned* ctr = nullptr) {
;     ...
;     auto publish = [&](int si) { if (tid == 0) { int wg = -1;
;             if (ticket < rng_cnt(xcd)) wg = rng_start(xcd) + ticket;
;             else { for (int k = 1; k < 8; ++k) { const int x2 = (xcd + k) & 7; const int t2 = (int)__hip_atomic_fetch_add(ctr + x2 * 16, 1u, __ATOMIC_RELAXED, __HIP_MEMORY_SCOPE_AGENT); if (t2 < rng_cnt(x2)) { wg = rng_start(x2) + t2; break; } } }
;             slot[si] = wg; } };
;     ...
;             PG8_LDB(B0, 1, 0); PG8_SCHED; PG8_LDA(At, 1, 0); PG8_STAGE(PG8_SA(0, 1), a2 + hstepA, voffA);
;             PG8_WAIT_L(8); PG8_BAR; PG8_WAIT_L(0); PG8_MMA(0, 0, At, B0); PG8_BAR; PG8_SCHED;
;             PG8_LDB(B1, 1, 1); PG8_STAGE(PG8_SB(1, 0), b3, voffB);
;             PG8_BAR; PG8_WAIT_L(0); PG8_MMA(0, 1, At, B1); PG8_BAR;
;             PG8_LDA(At, 1, 1); PG8_STAGE(PG8_SA(1, 0), a3, voffA);
;             PG8_BAR; PG8_WAIT_L(0); PG8_MMA(1, 0, At, B0); PG8_BAR; PG8_SCHED;
;             if (DYN && t == 0) publish((ui + 1) & 1);
;             PG8_STAGE(PG8_SB(1, 1), b3 + hstepB, voffB);
;             PG8_WAIT_V(6); PG8_BAR; PG8_MMA(1, 1, At, B1); PG8_BAR;
	ds_read_b128 v[170:173], v212 offset:49152
	ds_read_b128 v[174:177], v212 offset:50176
	ds_read_b128 v[162:165], v212 offset:51200
	ds_read_b128 v[166:169], v212 offset:52224
	ds_read_b128 v[154:157], v212 offset:53248
	ds_read_b128 v[158:161], v212 offset:54272
	ds_read_b128 v[146:149], v212 offset:55296
	ds_read_b128 v[150:153], v212 offset:56320
	global_load_lds_dwordx4 v[244:245], off
	v_lshl_add_u64 v[244:245], s[38:39], 0, v[180:181]
	s_mov_b32 m0, s87
	s_nop 0
	global_load_lds_dwordx4 v[244:245], off
	s_barrier
	s_waitcnt lgkmcnt(0)
	s_setprio 1
	s_waitcnt lgkmcnt(0)
	v_mfma_f32_16x16x32_bf16 v[62:65], v[196:199], v[170:173], v[62:65]
	v_mfma_f32_16x16x32_bf16 v[58:61], v[218:221], v[170:173], v[58:61]
	v_mfma_f32_16x16x32_bf16 v[54:57], v[196:199], v[162:165], v[54:57]
	v_mfma_f32_16x16x32_bf16 v[50:53], v[218:221], v[162:165], v[50:53]
	v_mfma_f32_16x16x32_bf16 v[46:49], v[196:199], v[154:157], v[46:49]
	v_mfma_f32_16x16x32_bf16 v[42:45], v[218:221], v[154:157], v[42:45]
	v_mfma_f32_16x16x32_bf16 v[38:41], v[196:199], v[146:149], v[38:41]
	v_mfma_f32_16x16x32_bf16 v[34:37], v[218:221], v[146:149], v[34:37]
	v_mfma_f32_16x16x32_bf16 v[62:65], v[214:217], v[174:177], v[62:65]
	v_mfma_f32_16x16x32_bf16 v[58:61], v[232:235], v[174:177], v[58:61]
	v_mfma_f32_16x16x32_bf16 v[54:57], v[214:217], v[166:169], v[54:57]
	v_mfma_f32_16x16x32_bf16 v[50:53], v[232:235], v[166:169], v[50:53]
	v_mfma_f32_16x16x32_bf16 v[46:49], v[214:217], v[158:161], v[46:49]
	v_mfma_f32_16x16x32_bf16 v[42:45], v[232:235], v[158:161], v[42:45]
	v_mfma_f32_16x16x32_bf16 v[38:41], v[214:217], v[150:153], v[38:41]
	v_mfma_f32_16x16x32_bf16 v[34:37], v[232:235], v[150:153], v[34:37]
	s_setprio 0
	s_barrier
	v_or_b32_e32 v196, s3, v187
	v_cmp_eq_u32_e64 s[38:39], 0, v196
	s_and_saveexec_b64 s[42:43], s[38:39]
	s_cbranch_execz .LBB0_505
	v_readlane_b32 s0, v254, 49
	v_cmp_lt_i32_e32 vcc, 0x287, v189
	s_nop 1
	v_add_u32_e32 v213, s0, v189
	v_mov_b32_e32 v214, v213
	s_and_saveexec_b64 s[46:47], vcc
	s_cbranch_execz .LBB0_504
	v_mov_b64_e32 v[196:197], s[50:51]
	flat_atomic_add v196, v[196:197], v224 sc0
	s_movk_i32 s0, 0x287
	s_waitcnt vmcnt(0) lgkmcnt(0)
	v_cmp_lt_i32_e64 s[38:39], s0, v196
	v_add_u32_e32 v214, s80, v196
	s_and_saveexec_b64 s[0:1], s[38:39]
	s_cbranch_execz .LBB0_503
	v_mov_b64_e32 v[196:197], s[54:55]
	flat_atomic_add v196, v[196:197], v224 sc0
	s_movk_i32 s4, 0x287
	s_waitcnt vmcnt(0) lgkmcnt(0)
	v_cmp_lt_i32_e64 s[38:39], s4, v196
	v_add_u32_e32 v214, s82, v196
	s_and_saveexec_b64 s[60:61], s[38:39]
	s_cbranch_execz .LBB0_502
	v_mov_b64_e32 v[196:197], s[58:59]
	flat_atomic_add v196, v[196:197], v224 sc0
	s_waitcnt vmcnt(0) lgkmcnt(0)
	v_cmp_lt_i32_e64 s[38:39], s4, v196
	v_add_u32_e32 v214, s17, v196
	s_and_saveexec_b64 s[62:63], s[38:39]
	s_cbranch_execz .LBB0_501
	v_mov_b64_e32 v[196:197], s[90:91]
	flat_atomic_add v196, v[196:197], v224 sc0
	s_waitcnt vmcnt(0) lgkmcnt(0)
	v_cmp_lt_i32_e64 s[38:39], s4, v196
	v_add_u32_e32 v214, s23, v196
	s_and_saveexec_b64 s[64:65], s[38:39]
	s_cbranch_execz .LBB0_500
	v_readlane_b32 s4, v255, 0
	v_readlane_b32 s5, v255, 1
	s_nop 1
	v_mov_b64_e32 v[196:197], s[4:5]
	flat_atomic_add v196, v[196:197], v224 sc0
	s_movk_i32 s4, 0x287
	s_waitcnt vmcnt(0) lgkmcnt(0)
	v_cmp_lt_i32_e64 s[38:39], s4, v196
	v_readlane_b32 s4, v255, 2
	s_nop 1
	v_add_u32_e32 v214, s4, v196
	s_and_saveexec_b64 s[68:69], s[38:39]
	s_cbranch_execz .LBB0_499
	v_readlane_b32 s4, v255, 4
	v_readlane_b32 s5, v255, 5
	s_nop 1
	v_mov_b64_e32 v[196:197], s[4:5]
	flat_atomic_add v196, v[196:197], v224 sc0
	s_movk_i32 s4, 0x287
	s_waitcnt vmcnt(0) lgkmcnt(0)
	v_cmp_lt_i32_e64 s[38:39], s4, v196
	v_readlane_b32 s4, v255, 6
	s_nop 1
	v_add_u32_e32 v214, s4, v196
	s_and_saveexec_b64 s[70:71], s[38:39]
	s_cbranch_execz .LBB0_498
	v_readlane_b32 s4, v255, 8
	v_readlane_b32 s5, v255, 9
	s_nop 1
	v_mov_b64_e32 v[196:197], s[4:5]
	flat_atomic_add v196, v[196:197], v224 sc0
	v_readlane_b32 s4, v255, 10
	s_waitcnt vmcnt(0) lgkmcnt(0)
	s_nop 0
	v_add_u32_e32 v197, s4, v196
	s_movk_i32 s4, 0x288
	v_cmp_gt_i32_e64 s[38:39], s4, v196
	s_nop 1
	v_cndmask_b32_e64 v214, -1, v197, s[38:39]
	s_branch .LBB0_498

; #define PG8_STAGE(bufoff, gbase, voff) do { _Pragma("unroll") for (int _i = 0; _i < 2; ++_i) \
;         __builtin_amdgcn_global_load_lds((const unsigned*)((const char*)(gbase) + (voff)[_i]), (LAS unsigned*)(lds + (bufoff) + ldsw + _i * 8192), 16, 0, 0); } while (0)
; #define PG8_LDA(dst, b, h) do { _Pragma("unroll") for (int m = 0; m < 4; ++m) _Pragma("unroll") for (int k = 0; k < 2; ++k) dst[m][k] = *(const LAS bf16x8*)(lds + PG8_SA(b, h) + aoff + m * 2048 + k * 1024); } while (0)
; #define PG8_LDB(dst, b, h) do { _Pragma("unroll") for (int n = 0; n < 2; ++n) _Pragma("unroll") for (int k = 0; k < 2; ++k) dst[n][k] = *(const LAS bf16x8*)(lds + PG8_SB(b, h) + boff + n * 2048 + k * 1024); } while (0)
; #define PG8_WAIT_V(n) asm volatile("s_waitcnt vmcnt(" #n ")" ::: "memory")
; template <class Epi, bool DYN = false>
; __device__ __forceinline__ void gemm_phase(LAS unsigned char* lds, const Gemm g, const Epi& E, int wave, unsigned* ctr = nullptr) {
;     ...
;             const bool last = (t == nt - 2);
;             if (DYN && last) { const int nw = __builtin_amdgcn_readfirstlane(slot[(ui + 1) & 1]); has_next = nw >= 0;
;                 if (has_next) { decode(nw, nxt); nA = (const char*)g.A + (size_t)nxt.pm * tstepA; nB = (const char*)g.Bt + (size_t)nxt.pn * tstepB; } }
;             const char* a1 = cA + (size_t)(t + 1) * kstepA;
;             const char* a2 = last ? nA : cA + (size_t)(t + 2) * kstepA; const char* b2 = last ? nB : cB + (size_t)(t + 2) * kstepB;
;             const char* a3 = a2 + kstepA; const char* b3 = b2 + kstepB;
;             PG8_LDB(B0, 0, 0); PG8_SCHED; PG8_LDA(At, 0, 0); PG8_STAGE(PG8_SA(1, 1), a1 + hstepA, voffA);
;             PG8_WAIT_L(8); PG8_BAR; PG8_WAIT_L(0); PG8_MMA(0, 0, At, B0); PG8_BAR; PG8_SCHED;
;             PG8_LDB(B1, 0, 1); PG8_STAGE(PG8_SB(0, 0), b2, voffB);
;             PG8_BAR; PG8_WAIT_L(0); PG8_MMA(0, 1, At, B1); PG8_BAR;
;             PG8_LDA(At, 0, 1); PG8_STAGE(PG8_SA(0, 0), a2, voffA);
;             PG8_BAR; PG8_WAIT_L(0); PG8_MMA(1, 0, At, B0); PG8_BAR; PG8_SCHED;
;             PG8_STAGE(PG8_SB(0, 1), b2 + hstepB, voffB);
;             PG8_WAIT_V(6); PG8_BAR; PG8_MMA(1, 1, At, B1); PG8_BAR;
;             PG8_LDB(B0, 1, 0); PG8_SCHED; PG8_LDA(At, 1, 0); PG8_STAGE(PG8_SA(0, 1), a2 + hstepA, voffA);
;             PG8_WAIT_L(8); PG8_BAR; PG8_WAIT_L(0); PG8_MMA(0, 0, At, B0); PG8_BAR; PG8_SCHED;
.LBB0_852:
	s_add_i32 s10, s10, 2
	s_add_u32 s0, s62, s68
	s_addc_u32 s1, s63, s69
	s_add_u32 s38, s0, 0x10000
	s_addc_u32 s39, s1, 0
	s_and_b64 s[0:1], s[70:71], exec
	s_cselect_b32 s73, s47, s39
	s_cselect_b32 s72, s46, s38
	s_add_u32 s74, s7, s68
	s_addc_u32 s75, s8, s69
	s_add_u32 s38, s72, 0x8000
	s_addc_u32 s39, s73, 0
	s_add_i32 s76, 0, 0x10000
	v_add_u32_e32 v142, s76, v200
	ds_read_b128 v[130:133], v142
	ds_read_b128 v[134:137], v142 offset:1024
	ds_read_b128 v[138:141], v142 offset:2048
	ds_read_b128 v[142:145], v142 offset:3072
	s_and_b64 s[0:1], s[70:71], exec
	s_cselect_b32 s71, s27, s75
	s_cselect_b32 s70, s26, s74
	v_lshl_add_u64 v[196:197], v[190:191], 0, s[68:69]
	s_add_i32 m0, s33, 0xc000
	ds_read_b128 v[146:149], v202
	ds_read_b128 v[150:153], v202 offset:1024
	ds_read_b128 v[154:157], v202 offset:2048
	ds_read_b128 v[158:161], v202 offset:3072
	ds_read_b128 v[162:165], v202 offset:4096
	ds_read_b128 v[166:169], v202 offset:5120
	ds_read_b128 v[170:173], v202 offset:6144
	ds_read_b128 v[174:177], v202 offset:7168
	global_load_lds_dwordx4 v[196:197], off
	v_lshl_add_u64 v[196:197], v[188:189], 0, s[68:69]
	s_add_i32 m0, s33, 0xe000
	s_nop 0
	global_load_lds_dwordx4 v[196:197], off
	s_waitcnt lgkmcnt(8)
	s_barrier
	s_waitcnt lgkmcnt(0)
	s_setprio 1
	s_waitcnt lgkmcnt(0)
	v_mfma_f32_16x16x32_bf16 v[126:129], v[130:133], v[146:149], v[126:129]
	v_mfma_f32_16x16x32_bf16 v[122:125], v[138:141], v[146:149], v[122:125]
	v_mfma_f32_16x16x32_bf16 v[118:121], v[130:133], v[154:157], v[118:121]
	v_mfma_f32_16x16x32_bf16 v[114:117], v[138:141], v[154:157], v[114:117]
	v_mfma_f32_16x16x32_bf16 v[110:113], v[130:133], v[162:165], v[110:113]
	v_mfma_f32_16x16x32_bf16 v[106:109], v[138:141], v[162:165], v[106:109]
	v_mfma_f32_16x16x32_bf16 v[102:105], v[130:133], v[170:173], v[102:105]
	v_mfma_f32_16x16x32_bf16 v[94:97], v[138:141], v[170:173], v[94:97]
	v_mfma_f32_16x16x32_bf16 v[126:129], v[134:137], v[150:153], v[126:129]
	v_mfma_f32_16x16x32_bf16 v[122:125], v[142:145], v[150:153], v[122:125]
	v_mfma_f32_16x16x32_bf16 v[118:121], v[134:137], v[158:161], v[118:121]
	v_mfma_f32_16x16x32_bf16 v[114:117], v[142:145], v[158:161], v[114:117]
	v_mfma_f32_16x16x32_bf16 v[110:113], v[134:137], v[166:169], v[110:113]
	v_mfma_f32_16x16x32_bf16 v[106:109], v[142:145], v[166:169], v[106:109]
	v_mfma_f32_16x16x32_bf16 v[102:105], v[134:137], v[174:177], v[102:105]
	v_mfma_f32_16x16x32_bf16 v[94:97], v[142:145], v[174:177], v[94:97]
	s_setprio 0
	s_barrier
	s_add_i32 s74, 0, 0x14000
	s_add_i32 s0, s76, s28
	v_add_u32_e32 v212, s74, v200
	v_lshl_add_u64 v[216:217], s[70:71], 0, v[0:1]
	s_mov_b32 m0, s0
	ds_read_b128 v[196:199], v212
	ds_read_b128 v[204:207], v212 offset:1024
	ds_read_b128 v[208:211], v212 offset:2048
	ds_read_b128 v[212:215], v212 offset:3072
	global_load_lds_dwordx4 v[216:217], off
	v_lshl_add_u64 v[216:217], s[70:71], 0, v[182:183]
	s_add_i32 m0, s0, 0x2000
	s_nop 0
	global_load_lds_dwordx4 v[216:217], off
	s_barrier
	s_waitcnt lgkmcnt(0)
	s_setprio 1
	s_waitcnt lgkmcnt(0)
	v_mfma_f32_16x16x32_bf16 v[90:93], v[196:199], v[146:149], v[90:93]
	v_mfma_f32_16x16x32_bf16 v[82:85], v[208:211], v[146:149], v[82:85]
	v_mfma_f32_16x16x32_bf16 v[74:77], v[196:199], v[154:157], v[74:77]
	v_mfma_f32_16x16x32_bf16 v[66:69], v[208:211], v[154:157], v[66:69]
	v_mfma_f32_16x16x32_bf16 v[58:61], v[196:199], v[162:165], v[58:61]
	v_mfma_f32_16x16x32_bf16 v[50:53], v[208:211], v[162:165], v[50:53]
	v_mfma_f32_16x16x32_bf16 v[42:45], v[196:199], v[170:173], v[42:45]
	v_mfma_f32_16x16x32_bf16 v[38:41], v[208:211], v[170:173], v[38:41]
	v_mfma_f32_16x16x32_bf16 v[90:93], v[204:207], v[150:153], v[90:93]
	v_mfma_f32_16x16x32_bf16 v[82:85], v[212:215], v[150:153], v[82:85]
	v_mfma_f32_16x16x32_bf16 v[74:77], v[204:207], v[158:161], v[74:77]
	v_mfma_f32_16x16x32_bf16 v[66:69], v[212:215], v[158:161], v[66:69]
	v_mfma_f32_16x16x32_bf16 v[58:61], v[204:207], v[166:169], v[58:61]
	v_mfma_f32_16x16x32_bf16 v[50:53], v[212:215], v[166:169], v[50:53]
	v_mfma_f32_16x16x32_bf16 v[42:45], v[204:207], v[174:177], v[42:45]
	v_mfma_f32_16x16x32_bf16 v[38:41], v[212:215], v[174:177], v[38:41]
	s_setprio 0
	s_mov_b32 m0, s33
	v_lshl_add_u64 v[216:217], s[72:73], 0, v[178:179]
	s_barrier
	ds_read_b128 v[146:149], v202 offset:16384
	ds_read_b128 v[150:153], v202 offset:17408
	ds_read_b128 v[154:157], v202 offset:18432
	ds_read_b128 v[158:161], v202 offset:19456
	ds_read_b128 v[162:165], v202 offset:20480
	ds_read_b128 v[166:169], v202 offset:21504
	ds_read_b128 v[170:173], v202 offset:22528
	ds_read_b128 v[174:177], v202 offset:23552
	global_load_lds_dwordx4 v[216:217], off
	v_lshl_add_u64 v[216:217], s[72:73], 0, v[180:181]
	s_mov_b32 m0, s48
	s_nop 0
	global_load_lds_dwordx4 v[216:217], off
	s_barrier
	s_waitcnt lgkmcnt(0)
	s_setprio 1
	s_waitcnt lgkmcnt(0)
	v_mfma_f32_16x16x32_bf16 v[34:37], v[130:133], v[146:149], v[34:37]
	v_mfma_f32_16x16x32_bf16 v[26:29], v[138:141], v[146:149], v[26:29]
	v_mfma_f32_16x16x32_bf16 v[22:25], v[130:133], v[154:157], v[22:25]
	v_mfma_f32_16x16x32_bf16 v[18:21], v[138:141], v[154:157], v[18:21]
	v_mfma_f32_16x16x32_bf16 v[14:17], v[130:133], v[162:165], v[14:17]
	v_mfma_f32_16x16x32_bf16 v[10:13], v[138:141], v[162:165], v[10:13]
	v_mfma_f32_16x16x32_bf16 v[6:9], v[130:133], v[170:173], v[6:9]
	v_mfma_f32_16x16x32_bf16 v[2:5], v[138:141], v[170:173], v[2:5]
	v_mfma_f32_16x16x32_bf16 v[34:37], v[134:137], v[150:153], v[34:37]
	v_mfma_f32_16x16x32_bf16 v[26:29], v[142:145], v[150:153], v[26:29]
	v_mfma_f32_16x16x32_bf16 v[22:25], v[134:137], v[158:161], v[22:25]
	v_mfma_f32_16x16x32_bf16 v[18:21], v[142:145], v[158:161], v[18:21]
	v_mfma_f32_16x16x32_bf16 v[14:17], v[134:137], v[166:169], v[14:17]
	v_mfma_f32_16x16x32_bf16 v[10:13], v[142:145], v[166:169], v[10:13]
	v_mfma_f32_16x16x32_bf16 v[6:9], v[134:137], v[174:177], v[6:9]
	v_mfma_f32_16x16x32_bf16 v[2:5], v[142:145], v[174:177], v[2:5]
	s_setprio 0
	s_barrier
; #define PG8_STAGE(bufoff, gbase, voff) do { _Pragma("unroll") for (int _i = 0; _i < 2; ++_i) \
;         __builtin_amdgcn_global_load_lds((const unsigned*)((const char*)(gbase) + (voff)[_i]), (LAS unsigned*)(lds + (bufoff) + ldsw + _i * 8192), 16, 0, 0); } while (0)
; #define PG8_LDA(dst, b, h) do { _Pragma("unroll") for (int m = 0; m < 4; ++m) _Pragma("unroll") for (int k = 0; k < 2; ++k) dst[m][k] = *(const LAS bf16x8*)(lds + PG8_SA(b, h) + aoff + m * 2048 + k * 1024); } while (0)
; #define PG8_LDB(dst, b, h) do { _Pragma("unroll") for (int n = 0; n < 2; ++n) _Pragma("unroll") for (int k = 0; k < 2; ++k) dst[n][k] = *(const LAS bf16x8*)(lds + PG8_SB(b, h) + boff + n * 2048 + k * 1024); } while (0)
; #define PG8_MMA(ai, bj, At, Bt) do { __builtin_amdgcn_s_setprio(1); _Pragma("unroll") for (int m = 0; m < 4; ++m) _Pragma("unroll") for (int n = 0; n < 2; ++n) _Pragma("unroll") for (int k = 0; k < 2; ++k) \
;         acc[ai][bj][m][n] = __builtin_amdgcn_mfma_f32_16x16x32_bf16(Bt[n][k], At[m][k], acc[ai][bj][m][n], 0, 0, 0); __builtin_amdgcn_s_setprio(0); } while (0)
; #define PG8_WAIT_V(n) asm volatile("s_waitcnt vmcnt(" #n ")" ::: "memory")
; #define PG8_WAIT_L(n) asm volatile("s_waitcnt lgkmcnt(" #n ")" ::: "memory")
; #define PG8_BAR __builtin_amdgcn_s_barrier()
; #define PG8_SCHED __builtin_amdgcn_sched_barrier(0)
; template <class Epi, bool DYN = false>
; __device__ __forceinline__ void gemm_phase(LAS unsigned char* lds, const Gemm g, const Epi& E, int wave, unsigned* ctr = nullptr) {
;     ...
;             PG8_LDA(At, 0, 1); PG8_STAGE(PG8_SA(0, 0), a2, voffA);
;             PG8_BAR; PG8_WAIT_L(0); PG8_MMA(1, 0, At, B0); PG8_BAR; PG8_SCHED;
;             PG8_STAGE(PG8_SB(0, 1), b2 + hstepB, voffB);
;             PG8_WAIT_V(6); PG8_BAR; PG8_MMA(1, 1, At, B1); PG8_BAR;
;             PG8_LDB(B0, 1, 0); PG8_SCHED; PG8_LDA(At, 1, 0); PG8_STAGE(PG8_SA(0, 1), a2 + hstepA, voffA);
;             PG8_WAIT_L(8); PG8_BAR; PG8_WAIT_L(0); PG8_MMA(0, 0, At, B0); PG8_BAR; PG8_SCHED;
;             PG8_LDB(B1, 1, 1); PG8_STAGE(PG8_SB(1, 0), b3, voffB);
;             PG8_BAR; PG8_WAIT_L(0); PG8_MMA(0, 1, At, B1); PG8_BAR;
;             PG8_LDA(At, 1, 1); PG8_STAGE(PG8_SA(1, 0), a3, voffA);
;             PG8_BAR; PG8_WAIT_L(0); PG8_MMA(1, 0, At, B0); PG8_BAR; PG8_SCHED;
	s_add_u32 s0, s70, 0x4000
	s_addc_u32 s1, s71, 0
	s_add_i32 s74, s74, s28
	v_lshl_add_u64 v[130:131], s[0:1], 0, v[0:1]
	s_mov_b32 m0, s74
	s_nop 0
	global_load_lds_dwordx4 v[130:131], off
	v_lshl_add_u64 v[130:131], s[0:1], 0, v[182:183]
	s_add_i32 m0, s74, 0x2000
	s_nop 0
	global_load_lds_dwordx4 v[130:131], off
	s_waitcnt vmcnt(6)
	s_barrier
	s_setprio 1
	v_mfma_f32_16x16x32_bf16 v[98:101], v[196:199], v[146:149], v[98:101]
	v_mfma_f32_16x16x32_bf16 v[86:89], v[208:211], v[146:149], v[86:89]
	v_mfma_f32_16x16x32_bf16 v[78:81], v[196:199], v[154:157], v[78:81]
	v_mfma_f32_16x16x32_bf16 v[70:73], v[208:211], v[154:157], v[70:73]
	v_mfma_f32_16x16x32_bf16 v[62:65], v[196:199], v[162:165], v[62:65]
	v_mfma_f32_16x16x32_bf16 v[54:57], v[208:211], v[162:165], v[54:57]
	v_mfma_f32_16x16x32_bf16 v[46:49], v[196:199], v[170:173], v[46:49]
	v_mfma_f32_16x16x32_bf16 v[30:33], v[208:211], v[170:173], v[30:33]
	v_mfma_f32_16x16x32_bf16 v[98:101], v[204:207], v[150:153], v[98:101]
	v_mfma_f32_16x16x32_bf16 v[86:89], v[212:215], v[150:153], v[86:89]
	v_mfma_f32_16x16x32_bf16 v[78:81], v[204:207], v[158:161], v[78:81]
	v_mfma_f32_16x16x32_bf16 v[70:73], v[212:215], v[158:161], v[70:73]
	v_mfma_f32_16x16x32_bf16 v[62:65], v[204:207], v[166:169], v[62:65]
	v_mfma_f32_16x16x32_bf16 v[54:57], v[212:215], v[166:169], v[54:57]
	v_mfma_f32_16x16x32_bf16 v[46:49], v[204:207], v[174:177], v[46:49]
	v_mfma_f32_16x16x32_bf16 v[30:33], v[212:215], v[174:177], v[30:33]
	s_setprio 0
	s_add_i32 s74, 0, 0x18000
	v_add_u32_e32 v130, s74, v200
	s_barrier
	ds_read_b128 v[196:199], v130
	ds_read_b128 v[204:207], v130 offset:1024
	ds_read_b128 v[208:211], v130 offset:2048
	ds_read_b128 v[212:215], v130 offset:3072
	s_add_u32 s0, s72, 0x4000
	s_addc_u32 s1, s73, 0
	s_mov_b32 m0, s86
	v_lshl_add_u64 v[130:131], s[0:1], 0, v[178:179]
	ds_read_b128 v[146:149], v202 offset:32768
	ds_read_b128 v[150:153], v202 offset:33792
	ds_read_b128 v[154:157], v202 offset:34816
	ds_read_b128 v[158:161], v202 offset:35840
	ds_read_b128 v[162:165], v202 offset:36864
	ds_read_b128 v[166:169], v202 offset:37888
	ds_read_b128 v[170:173], v202 offset:38912
	ds_read_b128 v[174:177], v202 offset:39936
	global_load_lds_dwordx4 v[130:131], off
	v_lshl_add_u64 v[130:131], s[0:1], 0, v[180:181]
	s_mov_b32 m0, s87
	s_nop 0
	global_load_lds_dwordx4 v[130:131], off
	s_waitcnt lgkmcnt(8)
	s_barrier
	s_waitcnt lgkmcnt(0)
	s_setprio 1
	s_waitcnt lgkmcnt(0)
	v_mfma_f32_16x16x32_bf16 v[126:129], v[196:199], v[146:149], v[126:129]
	v_mfma_f32_16x16x32_bf16 v[122:125], v[208:211], v[146:149], v[122:125]
	v_mfma_f32_16x16x32_bf16 v[118:121], v[196:199], v[154:157], v[118:121]
	v_mfma_f32_16x16x32_bf16 v[114:117], v[208:211], v[154:157], v[114:117]
	v_mfma_f32_16x16x32_bf16 v[110:113], v[196:199], v[162:165], v[110:113]
	v_mfma_f32_16x16x32_bf16 v[106:109], v[208:211], v[162:165], v[106:109]
	v_mfma_f32_16x16x32_bf16 v[102:105], v[196:199], v[170:173], v[102:105]
	v_mfma_f32_16x16x32_bf16 v[94:97], v[208:211], v[170:173], v[94:97]
	v_mfma_f32_16x16x32_bf16 v[126:129], v[204:207], v[150:153], v[126:129]
	v_mfma_f32_16x16x32_bf16 v[122:125], v[212:215], v[150:153], v[122:125]
	v_mfma_f32_16x16x32_bf16 v[118:121], v[204:207], v[158:161], v[118:121]
	v_mfma_f32_16x16x32_bf16 v[114:117], v[212:215], v[158:161], v[114:117]
	v_mfma_f32_16x16x32_bf16 v[110:113], v[204:207], v[166:169], v[110:113]
	v_mfma_f32_16x16x32_bf16 v[106:109], v[212:215], v[166:169], v[106:109]
	v_mfma_f32_16x16x32_bf16 v[102:105], v[204:207], v[174:177], v[102:105]
	v_mfma_f32_16x16x32_bf16 v[94:97], v[212:215], v[174:177], v[94:97]
	s_setprio 0
	s_barrier
	s_add_u32 s0, s70, 0x8000
	v_add_u32_e32 v130, 0, v200
	s_addc_u32 s1, s71, 0
	s_add_i32 s72, s74, s28
	v_add_u32_e32 v142, 0x1c000, v130
	v_lshl_add_u64 v[216:217], s[0:1], 0, v[0:1]
	s_mov_b32 m0, s72
	ds_read_b128 v[130:133], v142
	ds_read_b128 v[134:137], v142 offset:1024
	ds_read_b128 v[138:141], v142 offset:2048
	ds_read_b128 v[142:145], v142 offset:3072
	global_load_lds_dwordx4 v[216:217], off
	v_lshl_add_u64 v[216:217], s[0:1], 0, v[182:183]
	s_add_i32 m0, s72, 0x2000
	s_nop 0
	global_load_lds_dwordx4 v[216:217], off
	s_barrier
; #define PG8_STAGE(bufoff, gbase, voff) do { _Pragma("unroll") for (int _i = 0; _i < 2; ++_i) \
;         __builtin_amdgcn_global_load_lds((const unsigned*)((const char*)(gbase) + (voff)[_i]), (LAS unsigned*)(lds + (bufoff) + ldsw + _i * 8192), 16, 0, 0); } while (0)
; #define PG8_LDA(dst, b, h) do { _Pragma("unroll") for (int m = 0; m < 4; ++m) _Pragma("unroll") for (int k = 0; k < 2; ++k) dst[m][k] = *(const LAS bf16x8*)(lds + PG8_SA(b, h) + aoff + m * 2048 + k * 1024); } while (0)
; #define PG8_MMA(ai, bj, At, Bt) do { __builtin_amdgcn_s_setprio(1); _Pragma("unroll") for (int m = 0; m < 4; ++m) _Pragma("unroll") for (int n = 0; n < 2; ++n) _Pragma("unroll") for (int k = 0; k < 2; ++k) \
;         acc[ai][bj][m][n] = __builtin_amdgcn_mfma_f32_16x16x32_bf16(Bt[n][k], At[m][k], acc[ai][bj][m][n], 0, 0, 0); __builtin_amdgcn_s_setprio(0); } while (0)
; #define PG8_WAIT_V(n) asm volatile("s_waitcnt vmcnt(" #n ")" ::: "memory")
; #define PG8_WAIT_L(n) asm volatile("s_waitcnt lgkmcnt(" #n ")" ::: "memory")
; #define PG8_BAR __builtin_amdgcn_s_barrier()
; #define PG8_SCHED __builtin_amdgcn_sched_barrier(0)
; template <class Epi, bool DYN = false>
; __device__ __forceinline__ void gemm_phase(LAS unsigned char* lds, const Gemm g, const Epi& E, int wave, unsigned* ctr = nullptr) {
;     ...
;     auto publish = [&](int si) { if (tid == 0) { int wg = -1;
;             if (ticket < rng_cnt(xcd)) wg = rng_start(xcd) + ticket;
;             else { for (int k = 1; k < 8; ++k) { const int x2 = (xcd + k) & 7; const int t2 = (int)__hip_atomic_fetch_add(ctr + x2 * 16, 1u, __ATOMIC_RELAXED, __HIP_MEMORY_SCOPE_AGENT); if (t2 < rng_cnt(x2)) { wg = rng_start(x2) + t2; break; } } }
;             slot[si] = wg; } };
;     ...
;             PG8_BAR; PG8_WAIT_L(0); PG8_MMA(0, 1, At, B1); PG8_BAR;
;             PG8_LDA(At, 1, 1); PG8_STAGE(PG8_SA(1, 0), a3, voffA);
;             PG8_BAR; PG8_WAIT_L(0); PG8_MMA(1, 0, At, B0); PG8_BAR; PG8_SCHED;
;             if (DYN && t == 0) publish((ui + 1) & 1);
;             PG8_STAGE(PG8_SB(1, 1), b3 + hstepB, voffB);
;             PG8_WAIT_V(6); PG8_BAR; PG8_MMA(1, 1, At, B1); PG8_BAR;
	s_waitcnt lgkmcnt(0)
	s_setprio 1
	s_waitcnt lgkmcnt(0)
	v_mfma_f32_16x16x32_bf16 v[90:93], v[130:133], v[146:149], v[90:93]
	v_mfma_f32_16x16x32_bf16 v[82:85], v[138:141], v[146:149], v[82:85]
	v_mfma_f32_16x16x32_bf16 v[74:77], v[130:133], v[154:157], v[74:77]
	v_mfma_f32_16x16x32_bf16 v[66:69], v[138:141], v[154:157], v[66:69]
	v_mfma_f32_16x16x32_bf16 v[58:61], v[130:133], v[162:165], v[58:61]
	v_mfma_f32_16x16x32_bf16 v[50:53], v[138:141], v[162:165], v[50:53]
	v_mfma_f32_16x16x32_bf16 v[42:45], v[130:133], v[170:173], v[42:45]
	v_mfma_f32_16x16x32_bf16 v[38:41], v[138:141], v[170:173], v[38:41]
	v_mfma_f32_16x16x32_bf16 v[90:93], v[134:137], v[150:153], v[90:93]
	v_mfma_f32_16x16x32_bf16 v[82:85], v[142:145], v[150:153], v[82:85]
	v_mfma_f32_16x16x32_bf16 v[74:77], v[134:137], v[158:161], v[74:77]
	v_mfma_f32_16x16x32_bf16 v[66:69], v[142:145], v[158:161], v[66:69]
	v_mfma_f32_16x16x32_bf16 v[58:61], v[134:137], v[166:169], v[58:61]
	v_mfma_f32_16x16x32_bf16 v[50:53], v[142:145], v[166:169], v[50:53]
	v_mfma_f32_16x16x32_bf16 v[42:45], v[134:137], v[174:177], v[42:45]
	v_mfma_f32_16x16x32_bf16 v[38:41], v[142:145], v[174:177], v[38:41]
	s_setprio 0
	s_mov_b32 m0, s88
	v_lshl_add_u64 v[216:217], s[38:39], 0, v[178:179]
	s_barrier
	ds_read_b128 v[170:173], v202 offset:49152
	ds_read_b128 v[174:177], v202 offset:50176
	ds_read_b128 v[162:165], v202 offset:51200
	ds_read_b128 v[166:169], v202 offset:52224
	ds_read_b128 v[154:157], v202 offset:53248
	ds_read_b128 v[158:161], v202 offset:54272
	ds_read_b128 v[146:149], v202 offset:55296
	ds_read_b128 v[150:153], v202 offset:56320
	global_load_lds_dwordx4 v[216:217], off
	v_lshl_add_u64 v[216:217], s[38:39], 0, v[180:181]
	s_mov_b32 m0, s89
	s_nop 0
	global_load_lds_dwordx4 v[216:217], off
	s_barrier
	s_waitcnt lgkmcnt(0)
	s_setprio 1
	s_waitcnt lgkmcnt(0)
	v_mfma_f32_16x16x32_bf16 v[34:37], v[196:199], v[170:173], v[34:37]
	v_mfma_f32_16x16x32_bf16 v[26:29], v[208:211], v[170:173], v[26:29]
	v_mfma_f32_16x16x32_bf16 v[22:25], v[196:199], v[162:165], v[22:25]
	v_mfma_f32_16x16x32_bf16 v[18:21], v[208:211], v[162:165], v[18:21]
	v_mfma_f32_16x16x32_bf16 v[14:17], v[196:199], v[154:157], v[14:17]
	v_mfma_f32_16x16x32_bf16 v[10:13], v[208:211], v[154:157], v[10:13]
	v_mfma_f32_16x16x32_bf16 v[6:9], v[196:199], v[146:149], v[6:9]
	v_mfma_f32_16x16x32_bf16 v[2:5], v[208:211], v[146:149], v[2:5]
	v_mfma_f32_16x16x32_bf16 v[34:37], v[204:207], v[174:177], v[34:37]
	v_mfma_f32_16x16x32_bf16 v[26:29], v[212:215], v[174:177], v[26:29]
	v_mfma_f32_16x16x32_bf16 v[22:25], v[204:207], v[166:169], v[22:25]
	v_mfma_f32_16x16x32_bf16 v[18:21], v[212:215], v[166:169], v[18:21]
	v_mfma_f32_16x16x32_bf16 v[14:17], v[204:207], v[158:161], v[14:17]
	v_mfma_f32_16x16x32_bf16 v[10:13], v[212:215], v[158:161], v[10:13]
	v_mfma_f32_16x16x32_bf16 v[6:9], v[204:207], v[150:153], v[6:9]
	v_mfma_f32_16x16x32_bf16 v[2:5], v[212:215], v[150:153], v[2:5]
	s_setprio 0
	s_barrier
	v_or_b32_e32 v196, s10, v192
	v_cmp_eq_u32_e64 s[38:39], 0, v196
	s_and_saveexec_b64 s[72:73], s[38:39]
	s_cbranch_execz .LBB0_847
	v_cmp_lt_i32_e32 vcc, s91, v193
	v_add_u32_e32 v203, s61, v193
	v_mov_b32_e32 v204, v203
	s_and_saveexec_b64 s[74:75], vcc
	s_cbranch_execz .LBB0_846
	v_mov_b64_e32 v[196:197], s[40:41]
	flat_atomic_add v196, v[196:197], v224 sc0
	s_waitcnt vmcnt(0) lgkmcnt(0)
	v_cmp_lt_i32_e64 s[38:39], s91, v196
	v_add_u32_e32 v204, s3, v196
	s_and_saveexec_b64 s[0:1], s[38:39]
	s_cbranch_execz .LBB0_845
	v_mov_b64_e32 v[196:197], s[42:43]
	flat_atomic_add v196, v[196:197], v224 sc0
	s_waitcnt vmcnt(0) lgkmcnt(0)
	v_cmp_lt_i32_e64 s[38:39], s91, v196
	v_add_u32_e32 v204, s2, v196
	s_and_saveexec_b64 s[76:77], s[38:39]
	s_cbranch_execz .LBB0_844
	v_mov_b64_e32 v[196:197], s[44:45]
	flat_atomic_add v196, v[196:197], v224 sc0
	s_waitcnt vmcnt(0) lgkmcnt(0)
	v_cmp_lt_i32_e64 s[38:39], s91, v196
	v_add_u32_e32 v204, s22, v196
	s_and_saveexec_b64 s[78:79], s[38:39]
	s_cbranch_execz .LBB0_843
	v_mov_b64_e32 v[196:197], s[50:51]
	flat_atomic_add v196, v[196:197], v224 sc0
	s_waitcnt vmcnt(0) lgkmcnt(0)
	v_cmp_lt_i32_e64 s[38:39], s91, v196
	v_add_u32_e32 v204, s23, v196
	s_and_saveexec_b64 s[80:81], s[38:39]
	s_cbranch_execz .LBB0_842
	v_mov_b64_e32 v[196:197], s[54:55]
	flat_atomic_add v196, v[196:197], v224 sc0
	s_movk_i32 s92, 0x60
	s_waitcnt vmcnt(0) lgkmcnt(0)
	v_cmp_lt_i32_e64 s[38:39], s91, v196
	v_add_u32_e32 v204, s60, v196
	s_and_saveexec_b64 s[82:83], s[38:39]
	s_cbranch_execz .LBB0_841
	v_mov_b64_e32 v[196:197], s[58:59]
	flat_atomic_add v196, v[196:197], v224 sc0
	v_readlane_b32 s84, v254, 52
	s_waitcnt vmcnt(0) lgkmcnt(0)
	v_cmp_lt_i32_e64 s[38:39], s91, v196
	v_add_u32_e32 v204, s84, v196
	s_and_saveexec_b64 s[84:85], s[38:39]
	s_cbranch_execz .LBB0_840
	v_readlane_b32 s38, v254, 54
	v_readlane_b32 s39, v254, 55
	s_nop 1
	v_mov_b64_e32 v[196:197], s[38:39]
	flat_atomic_add v196, v[196:197], v224 sc0
	v_readlane_b32 s38, v254, 56
	s_waitcnt vmcnt(0) lgkmcnt(0)
	s_nop 0
	v_add_u32_e32 v197, s38, v196
	v_cmp_gt_i32_e64 s[38:39], s92, v196
	s_nop 1
	v_cndmask_b32_e64 v204, -1, v197, s[38:39]
	s_branch .LBB0_840

; #define PG8_STAGE(bufoff, gbase, voff) do { _Pragma("unroll") for (int _i = 0; _i < 2; ++_i) \
;         __builtin_amdgcn_global_load_lds((const unsigned*)((const char*)(gbase) + (voff)[_i]), (LAS unsigned*)(lds + (bufoff) + ldsw + _i * 8192), 16, 0, 0); } while (0)
; #define PG8_LDA(dst, b, h) do { _Pragma("unroll") for (int m = 0; m < 4; ++m) _Pragma("unroll") for (int k = 0; k < 2; ++k) dst[m][k] = *(const LAS bf16x8*)(lds + PG8_SA(b, h) + aoff + m * 2048 + k * 1024); } while (0)
; #define PG8_LDB(dst, b, h) do { _Pragma("unroll") for (int n = 0; n < 2; ++n) _Pragma("unroll") for (int k = 0; k < 2; ++k) dst[n][k] = *(const LAS bf16x8*)(lds + PG8_SB(b, h) + boff + n * 2048 + k * 1024); } while (0)
; #define PG8_WAIT_V(n) asm volatile("s_waitcnt vmcnt(" #n ")" ::: "memory")
; template <class Epi, bool DYN = false>
; __device__ __forceinline__ void gemm_phase(LAS unsigned char* lds, const Gemm g, const Epi& E, int wave, unsigned* ctr = nullptr) {
;     ...
;             const bool last = (t == nt - 2);
;             if (DYN && last) { const int nw = __builtin_amdgcn_readfirstlane(slot[(ui + 1) & 1]); has_next = nw >= 0;
;                 if (has_next) { decode(nw, nxt); nA = (const char*)g.A + (size_t)nxt.pm * tstepA; nB = (const char*)g.Bt + (size_t)nxt.pn * tstepB; } }
;             const char* a1 = cA + (size_t)(t + 1) * kstepA;
;             const char* a2 = last ? nA : cA + (size_t)(t + 2) * kstepA; const char* b2 = last ? nB : cB + (size_t)(t + 2) * kstepB;
;             const char* a3 = a2 + kstepA; const char* b3 = b2 + kstepB;
;             PG8_LDB(B0, 0, 0); PG8_SCHED; PG8_LDA(At, 0, 0); PG8_STAGE(PG8_SA(1, 1), a1 + hstepA, voffA);
;             PG8_WAIT_L(8); PG8_BAR; PG8_WAIT_L(0); PG8_MMA(0, 0, At, B0); PG8_BAR; PG8_SCHED;
;             PG8_LDB(B1, 0, 1); PG8_STAGE(PG8_SB(0, 0), b2, voffB);
;             PG8_BAR; PG8_WAIT_L(0); PG8_MMA(0, 1, At, B1); PG8_BAR;
;             PG8_LDA(At, 0, 1); PG8_STAGE(PG8_SA(0, 0), a2, voffA);
;             PG8_BAR; PG8_WAIT_L(0); PG8_MMA(1, 0, At, B0); PG8_BAR; PG8_SCHED;
;             PG8_STAGE(PG8_SB(0, 1), b2 + hstepB, voffB);
;             PG8_WAIT_V(6); PG8_BAR; PG8_MMA(1, 1, At, B1); PG8_BAR;
;             PG8_LDB(B0, 1, 0); PG8_SCHED; PG8_LDA(At, 1, 0); PG8_STAGE(PG8_SA(0, 1), a2 + hstepA, voffA);
;             PG8_WAIT_L(8); PG8_BAR; PG8_WAIT_L(0); PG8_MMA(0, 0, At, B0); PG8_BAR; PG8_SCHED;
.LBB0_924:
	s_add_i32 s7, s7, 2
	s_add_u32 s0, s68, s46
	s_addc_u32 s1, s69, s47
	s_add_u32 s8, s0, 0x10000
	s_addc_u32 s9, s1, 0
	s_and_b64 s[0:1], s[74:75], exec
	s_cselect_b32 s77, s71, s9
	s_cselect_b32 s76, s70, s8
	s_add_u32 s8, s4, s46
	s_addc_u32 s9, s5, s47
	s_add_u32 s38, s76, 0x8000
	s_addc_u32 s39, s77, 0
	s_add_i32 s10, 0, 0x10000
	v_add_u32_e32 v0, s10, v214
	ds_read_b128 v[130:133], v0
	ds_read_b128 v[134:137], v0 offset:1024
	ds_read_b128 v[138:141], v0 offset:2048
	ds_read_b128 v[142:145], v0 offset:3072
	s_and_b64 s[0:1], s[74:75], exec
	s_cselect_b32 s75, s65, s9
	s_cselect_b32 s74, s64, s8
	v_lshl_add_u64 v[196:197], v[200:201], 0, s[46:47]
	s_add_i32 m0, s19, 0xc000
	ds_read_b128 v[146:149], v215
	ds_read_b128 v[150:153], v215 offset:1024
	ds_read_b128 v[154:157], v215 offset:2048
	ds_read_b128 v[158:161], v215 offset:3072
	ds_read_b128 v[162:165], v215 offset:4096
	ds_read_b128 v[166:169], v215 offset:5120
	ds_read_b128 v[170:173], v215 offset:6144
	ds_read_b128 v[174:177], v215 offset:7168
	global_load_lds_dwordx4 v[196:197], off
	v_lshl_add_u64 v[196:197], v[192:193], 0, s[46:47]
	s_add_i32 m0, s19, 0xe000
	s_nop 0
	global_load_lds_dwordx4 v[196:197], off
	s_waitcnt lgkmcnt(8)
	s_barrier
	s_waitcnt lgkmcnt(0)
	s_setprio 1
	s_waitcnt lgkmcnt(0)
	v_mfma_f32_16x16x32_bf16 v[2:5], v[130:133], v[146:149], v[2:5]
	v_mfma_f32_16x16x32_bf16 v[30:33], v[138:141], v[146:149], v[30:33]
	v_mfma_f32_16x16x32_bf16 v[26:29], v[130:133], v[154:157], v[26:29]
	v_mfma_f32_16x16x32_bf16 v[22:25], v[138:141], v[154:157], v[22:25]
	v_mfma_f32_16x16x32_bf16 v[18:21], v[130:133], v[162:165], v[18:21]
	v_mfma_f32_16x16x32_bf16 v[14:17], v[138:141], v[162:165], v[14:17]
	v_mfma_f32_16x16x32_bf16 v[10:13], v[130:133], v[170:173], v[10:13]
	v_mfma_f32_16x16x32_bf16 v[6:9], v[138:141], v[170:173], v[6:9]
	v_mfma_f32_16x16x32_bf16 v[2:5], v[134:137], v[150:153], v[2:5]
	v_mfma_f32_16x16x32_bf16 v[30:33], v[142:145], v[150:153], v[30:33]
	v_mfma_f32_16x16x32_bf16 v[26:29], v[134:137], v[158:161], v[26:29]
	v_mfma_f32_16x16x32_bf16 v[22:25], v[142:145], v[158:161], v[22:25]
	v_mfma_f32_16x16x32_bf16 v[18:21], v[134:137], v[166:169], v[18:21]
	v_mfma_f32_16x16x32_bf16 v[14:17], v[142:145], v[166:169], v[14:17]
	v_mfma_f32_16x16x32_bf16 v[10:13], v[134:137], v[174:177], v[10:13]
	v_mfma_f32_16x16x32_bf16 v[6:9], v[142:145], v[174:177], v[6:9]
	s_setprio 0
	s_barrier
	s_add_i32 s8, 0, 0x14000
	s_add_i32 s0, s10, s17
	v_add_u32_e32 v0, s8, v214
	v_lshl_add_u64 v[220:221], s[74:75], 0, v[180:181]
	s_mov_b32 m0, s0
	ds_read_b128 v[216:219], v0
	ds_read_b128 v[244:247], v0 offset:1024
	ds_read_b128 v[232:235], v0 offset:2048
	ds_read_b128 v[196:199], v0 offset:3072
	global_load_lds_dwordx4 v[220:221], off
	v_lshl_add_u64 v[220:221], s[74:75], 0, v[184:185]
	s_add_i32 m0, s0, 0x2000
	s_nop 0
	global_load_lds_dwordx4 v[220:221], off
	s_barrier
	s_waitcnt lgkmcnt(0)
	s_setprio 1
	s_waitcnt lgkmcnt(0)
	v_mfma_f32_16x16x32_bf16 v[94:97], v[216:219], v[146:149], v[94:97]
	v_mfma_f32_16x16x32_bf16 v[90:93], v[232:235], v[146:149], v[90:93]
	v_mfma_f32_16x16x32_bf16 v[86:89], v[216:219], v[154:157], v[86:89]
	v_mfma_f32_16x16x32_bf16 v[82:85], v[232:235], v[154:157], v[82:85]
	v_mfma_f32_16x16x32_bf16 v[78:81], v[216:219], v[162:165], v[78:81]
	v_mfma_f32_16x16x32_bf16 v[74:77], v[232:235], v[162:165], v[74:77]
	v_mfma_f32_16x16x32_bf16 v[70:73], v[216:219], v[170:173], v[70:73]
	v_mfma_f32_16x16x32_bf16 v[66:69], v[232:235], v[170:173], v[66:69]
	v_mfma_f32_16x16x32_bf16 v[94:97], v[244:247], v[150:153], v[94:97]
	v_mfma_f32_16x16x32_bf16 v[90:93], v[196:199], v[150:153], v[90:93]
	v_mfma_f32_16x16x32_bf16 v[86:89], v[244:247], v[158:161], v[86:89]
	v_mfma_f32_16x16x32_bf16 v[82:85], v[196:199], v[158:161], v[82:85]
	v_mfma_f32_16x16x32_bf16 v[78:81], v[244:247], v[166:169], v[78:81]
	v_mfma_f32_16x16x32_bf16 v[74:77], v[196:199], v[166:169], v[74:77]
	v_mfma_f32_16x16x32_bf16 v[70:73], v[244:247], v[174:177], v[70:73]
	v_mfma_f32_16x16x32_bf16 v[66:69], v[196:199], v[174:177], v[66:69]
	s_setprio 0
	s_mov_b32 m0, s19
	v_lshl_add_u64 v[220:221], s[76:77], 0, v[178:179]
	s_barrier
	ds_read_b128 v[146:149], v215 offset:16384
	ds_read_b128 v[150:153], v215 offset:17408
	ds_read_b128 v[154:157], v215 offset:18432
	ds_read_b128 v[158:161], v215 offset:19456
	ds_read_b128 v[162:165], v215 offset:20480
	ds_read_b128 v[166:169], v215 offset:21504
	ds_read_b128 v[170:173], v215 offset:22528
	ds_read_b128 v[174:177], v215 offset:23552
	global_load_lds_dwordx4 v[220:221], off
	v_lshl_add_u64 v[220:221], s[76:77], 0, v[182:183]
	s_mov_b32 m0, s23
	s_nop 0
	global_load_lds_dwordx4 v[220:221], off
	s_barrier
	s_waitcnt lgkmcnt(0)
	s_setprio 1
	s_waitcnt lgkmcnt(0)
	v_mfma_f32_16x16x32_bf16 v[62:65], v[130:133], v[146:149], v[62:65]
	v_mfma_f32_16x16x32_bf16 v[58:61], v[138:141], v[146:149], v[58:61]
	v_mfma_f32_16x16x32_bf16 v[54:57], v[130:133], v[154:157], v[54:57]
	v_mfma_f32_16x16x32_bf16 v[50:53], v[138:141], v[154:157], v[50:53]
	v_mfma_f32_16x16x32_bf16 v[46:49], v[130:133], v[162:165], v[46:49]
	v_mfma_f32_16x16x32_bf16 v[42:45], v[138:141], v[162:165], v[42:45]
	v_mfma_f32_16x16x32_bf16 v[38:41], v[130:133], v[170:173], v[38:41]
	v_mfma_f32_16x16x32_bf16 v[34:37], v[138:141], v[170:173], v[34:37]
	v_mfma_f32_16x16x32_bf16 v[62:65], v[134:137], v[150:153], v[62:65]
	v_mfma_f32_16x16x32_bf16 v[58:61], v[142:145], v[150:153], v[58:61]
	v_mfma_f32_16x16x32_bf16 v[54:57], v[134:137], v[158:161], v[54:57]
	v_mfma_f32_16x16x32_bf16 v[50:53], v[142:145], v[158:161], v[50:53]
	v_mfma_f32_16x16x32_bf16 v[46:49], v[134:137], v[166:169], v[46:49]
	v_mfma_f32_16x16x32_bf16 v[42:45], v[142:145], v[166:169], v[42:45]
	v_mfma_f32_16x16x32_bf16 v[38:41], v[134:137], v[174:177], v[38:41]
	v_mfma_f32_16x16x32_bf16 v[34:37], v[142:145], v[174:177], v[34:37]
	s_setprio 0
	s_barrier
; #define PG8_STAGE(bufoff, gbase, voff) do { _Pragma("unroll") for (int _i = 0; _i < 2; ++_i) \
;         __builtin_amdgcn_global_load_lds((const unsigned*)((const char*)(gbase) + (voff)[_i]), (LAS unsigned*)(lds + (bufoff) + ldsw + _i * 8192), 16, 0, 0); } while (0)
; #define PG8_LDA(dst, b, h) do { _Pragma("unroll") for (int m = 0; m < 4; ++m) _Pragma("unroll") for (int k = 0; k < 2; ++k) dst[m][k] = *(const LAS bf16x8*)(lds + PG8_SA(b, h) + aoff + m * 2048 + k * 1024); } while (0)
; #define PG8_LDB(dst, b, h) do { _Pragma("unroll") for (int n = 0; n < 2; ++n) _Pragma("unroll") for (int k = 0; k < 2; ++k) dst[n][k] = *(const LAS bf16x8*)(lds + PG8_SB(b, h) + boff + n * 2048 + k * 1024); } while (0)
; #define PG8_MMA(ai, bj, At, Bt) do { __builtin_amdgcn_s_setprio(1); _Pragma("unroll") for (int m = 0; m < 4; ++m) _Pragma("unroll") for (int n = 0; n < 2; ++n) _Pragma("unroll") for (int k = 0; k < 2; ++k) \
;         acc[ai][bj][m][n] = __builtin_amdgcn_mfma_f32_16x16x32_bf16(Bt[n][k], At[m][k], acc[ai][bj][m][n], 0, 0, 0); __builtin_amdgcn_s_setprio(0); } while (0)
; #define PG8_WAIT_V(n) asm volatile("s_waitcnt vmcnt(" #n ")" ::: "memory")
; #define PG8_WAIT_L(n) asm volatile("s_waitcnt lgkmcnt(" #n ")" ::: "memory")
; #define PG8_BAR __builtin_amdgcn_s_barrier()
; #define PG8_SCHED __builtin_amdgcn_sched_barrier(0)
; template <class Epi, bool DYN = false>
; __device__ __forceinline__ void gemm_phase(LAS unsigned char* lds, const Gemm g, const Epi& E, int wave, unsigned* ctr = nullptr) {
;     ...
;             PG8_LDA(At, 0, 1); PG8_STAGE(PG8_SA(0, 0), a2, voffA);
;             PG8_BAR; PG8_WAIT_L(0); PG8_MMA(1, 0, At, B0); PG8_BAR; PG8_SCHED;
;             PG8_STAGE(PG8_SB(0, 1), b2 + hstepB, voffB);
;             PG8_WAIT_V(6); PG8_BAR; PG8_MMA(1, 1, At, B1); PG8_BAR;
;             PG8_LDB(B0, 1, 0); PG8_SCHED; PG8_LDA(At, 1, 0); PG8_STAGE(PG8_SA(0, 1), a2 + hstepA, voffA);
;             PG8_WAIT_L(8); PG8_BAR; PG8_WAIT_L(0); PG8_MMA(0, 0, At, B0); PG8_BAR; PG8_SCHED;
;             PG8_LDB(B1, 1, 1); PG8_STAGE(PG8_SB(1, 0), b3, voffB);
;             PG8_BAR; PG8_WAIT_L(0); PG8_MMA(0, 1, At, B1); PG8_BAR;
;             PG8_LDA(At, 1, 1); PG8_STAGE(PG8_SA(1, 0), a3, voffA);
;             PG8_BAR; PG8_WAIT_L(0); PG8_MMA(1, 0, At, B0); PG8_BAR; PG8_SCHED;
	s_add_u32 s0, s74, 0x4000
	s_addc_u32 s1, s75, 0
	s_add_i32 s8, s8, s17
	v_lshl_add_u64 v[130:131], s[0:1], 0, v[180:181]
	s_mov_b32 m0, s8
	s_nop 0
	global_load_lds_dwordx4 v[130:131], off
	v_lshl_add_u64 v[130:131], s[0:1], 0, v[184:185]
	s_add_i32 m0, s8, 0x2000
	s_nop 0
	global_load_lds_dwordx4 v[130:131], off
	s_waitcnt vmcnt(6)
	s_barrier
	s_setprio 1
	v_mfma_f32_16x16x32_bf16 v[126:129], v[216:219], v[146:149], v[126:129]
	v_mfma_f32_16x16x32_bf16 v[122:125], v[232:235], v[146:149], v[122:125]
	v_mfma_f32_16x16x32_bf16 v[118:121], v[216:219], v[154:157], v[118:121]
	v_mfma_f32_16x16x32_bf16 v[114:117], v[232:235], v[154:157], v[114:117]
	v_mfma_f32_16x16x32_bf16 v[110:113], v[216:219], v[162:165], v[110:113]
	v_mfma_f32_16x16x32_bf16 v[106:109], v[232:235], v[162:165], v[106:109]
	v_mfma_f32_16x16x32_bf16 v[102:105], v[216:219], v[170:173], v[102:105]
	v_mfma_f32_16x16x32_bf16 v[98:101], v[232:235], v[170:173], v[98:101]
	v_mfma_f32_16x16x32_bf16 v[126:129], v[244:247], v[150:153], v[126:129]
	v_mfma_f32_16x16x32_bf16 v[122:125], v[196:199], v[150:153], v[122:125]
	v_mfma_f32_16x16x32_bf16 v[118:121], v[244:247], v[158:161], v[118:121]
	v_mfma_f32_16x16x32_bf16 v[114:117], v[196:199], v[158:161], v[114:117]
	v_mfma_f32_16x16x32_bf16 v[110:113], v[244:247], v[166:169], v[110:113]
	v_mfma_f32_16x16x32_bf16 v[106:109], v[196:199], v[166:169], v[106:109]
	v_mfma_f32_16x16x32_bf16 v[102:105], v[244:247], v[174:177], v[102:105]
	v_mfma_f32_16x16x32_bf16 v[98:101], v[196:199], v[174:177], v[98:101]
	s_setprio 0
	s_add_i32 s8, 0, 0x18000
	v_add_u32_e32 v0, s8, v214
	s_barrier
	ds_read_b128 v[196:199], v0
	ds_read_b128 v[216:219], v0 offset:1024
	ds_read_b128 v[232:235], v0 offset:2048
	ds_read_b128 v[244:247], v0 offset:3072
	s_add_u32 s0, s76, 0x4000
	s_addc_u32 s1, s77, 0
	s_mov_b32 m0, s27
	v_lshl_add_u64 v[130:131], s[0:1], 0, v[178:179]
	ds_read_b128 v[146:149], v215 offset:32768
	ds_read_b128 v[150:153], v215 offset:33792
	ds_read_b128 v[154:157], v215 offset:34816
	ds_read_b128 v[158:161], v215 offset:35840
	ds_read_b128 v[162:165], v215 offset:36864
	ds_read_b128 v[166:169], v215 offset:37888
	ds_read_b128 v[170:173], v215 offset:38912
	ds_read_b128 v[174:177], v215 offset:39936
	global_load_lds_dwordx4 v[130:131], off
	v_lshl_add_u64 v[130:131], s[0:1], 0, v[182:183]
	s_mov_b32 m0, s15
	s_nop 0
	global_load_lds_dwordx4 v[130:131], off
	s_waitcnt lgkmcnt(8)
	s_barrier
	s_waitcnt lgkmcnt(0)
	s_setprio 1
	s_waitcnt lgkmcnt(0)
	v_mfma_f32_16x16x32_bf16 v[2:5], v[196:199], v[146:149], v[2:5]
	v_mfma_f32_16x16x32_bf16 v[30:33], v[232:235], v[146:149], v[30:33]
	v_mfma_f32_16x16x32_bf16 v[26:29], v[196:199], v[154:157], v[26:29]
	v_mfma_f32_16x16x32_bf16 v[22:25], v[232:235], v[154:157], v[22:25]
	v_mfma_f32_16x16x32_bf16 v[18:21], v[196:199], v[162:165], v[18:21]
	v_mfma_f32_16x16x32_bf16 v[14:17], v[232:235], v[162:165], v[14:17]
	v_mfma_f32_16x16x32_bf16 v[10:13], v[196:199], v[170:173], v[10:13]
	v_mfma_f32_16x16x32_bf16 v[6:9], v[232:235], v[170:173], v[6:9]
	v_mfma_f32_16x16x32_bf16 v[2:5], v[216:219], v[150:153], v[2:5]
	v_mfma_f32_16x16x32_bf16 v[30:33], v[244:247], v[150:153], v[30:33]
	v_mfma_f32_16x16x32_bf16 v[26:29], v[216:219], v[158:161], v[26:29]
	v_mfma_f32_16x16x32_bf16 v[22:25], v[244:247], v[158:161], v[22:25]
	v_mfma_f32_16x16x32_bf16 v[18:21], v[216:219], v[166:169], v[18:21]
	v_mfma_f32_16x16x32_bf16 v[14:17], v[244:247], v[166:169], v[14:17]
	v_mfma_f32_16x16x32_bf16 v[10:13], v[216:219], v[174:177], v[10:13]
	v_mfma_f32_16x16x32_bf16 v[6:9], v[244:247], v[174:177], v[6:9]
	s_setprio 0
	s_barrier
	s_add_u32 s0, s74, 0x8000
	v_add_u32_e32 v0, 0, v214
	s_addc_u32 s1, s75, 0
	s_add_i32 s8, s8, s17
	v_add_u32_e32 v0, 0x1c000, v0
	v_lshl_add_u64 v[220:221], s[0:1], 0, v[180:181]
	s_mov_b32 m0, s8
	ds_read_b128 v[130:133], v0
	ds_read_b128 v[134:137], v0 offset:1024
	ds_read_b128 v[138:141], v0 offset:2048
	ds_read_b128 v[142:145], v0 offset:3072
	global_load_lds_dwordx4 v[220:221], off
	v_lshl_add_u64 v[220:221], s[0:1], 0, v[184:185]
	s_add_i32 m0, s8, 0x2000
	s_nop 0
	global_load_lds_dwordx4 v[220:221], off
	s_barrier
; #define PG8_STAGE(bufoff, gbase, voff) do { _Pragma("unroll") for (int _i = 0; _i < 2; ++_i) \
;         __builtin_amdgcn_global_load_lds((const unsigned*)((const char*)(gbase) + (voff)[_i]), (LAS unsigned*)(lds + (bufoff) + ldsw + _i * 8192), 16, 0, 0); } while (0)
; #define PG8_LDA(dst, b, h) do { _Pragma("unroll") for (int m = 0; m < 4; ++m) _Pragma("unroll") for (int k = 0; k < 2; ++k) dst[m][k] = *(const LAS bf16x8*)(lds + PG8_SA(b, h) + aoff + m * 2048 + k * 1024); } while (0)
; #define PG8_MMA(ai, bj, At, Bt) do { __builtin_amdgcn_s_setprio(1); _Pragma("unroll") for (int m = 0; m < 4; ++m) _Pragma("unroll") for (int n = 0; n < 2; ++n) _Pragma("unroll") for (int k = 0; k < 2; ++k) \
;         acc[ai][bj][m][n] = __builtin_amdgcn_mfma_f32_16x16x32_bf16(Bt[n][k], At[m][k], acc[ai][bj][m][n], 0, 0, 0); __builtin_amdgcn_s_setprio(0); } while (0)
; #define PG8_WAIT_V(n) asm volatile("s_waitcnt vmcnt(" #n ")" ::: "memory")
; #define PG8_WAIT_L(n) asm volatile("s_waitcnt lgkmcnt(" #n ")" ::: "memory")
; #define PG8_BAR __builtin_amdgcn_s_barrier()
; #define PG8_SCHED __builtin_amdgcn_sched_barrier(0)
; template <class Epi, bool DYN = false>
; __device__ __forceinline__ void gemm_phase(LAS unsigned char* lds, const Gemm g, const Epi& E, int wave, unsigned* ctr = nullptr) {
;     ...
;     auto publish = [&](int si) { if (tid == 0) { int wg = -1;
;             if (ticket < rng_cnt(xcd)) wg = rng_start(xcd) + ticket;
;             else { for (int k = 1; k < 8; ++k) { const int x2 = (xcd + k) & 7; const int t2 = (int)__hip_atomic_fetch_add(ctr + x2 * 16, 1u, __ATOMIC_RELAXED, __HIP_MEMORY_SCOPE_AGENT); if (t2 < rng_cnt(x2)) { wg = rng_start(x2) + t2; break; } } }
;             slot[si] = wg; } };
;     ...
;             PG8_BAR; PG8_WAIT_L(0); PG8_MMA(0, 1, At, B1); PG8_BAR;
;             PG8_LDA(At, 1, 1); PG8_STAGE(PG8_SA(1, 0), a3, voffA);
;             PG8_BAR; PG8_WAIT_L(0); PG8_MMA(1, 0, At, B0); PG8_BAR; PG8_SCHED;
;             if (DYN && t == 0) publish((ui + 1) & 1);
;             PG8_STAGE(PG8_SB(1, 1), b3 + hstepB, voffB);
;             PG8_WAIT_V(6); PG8_BAR; PG8_MMA(1, 1, At, B1); PG8_BAR;
	s_waitcnt lgkmcnt(0)
	s_setprio 1
	s_waitcnt lgkmcnt(0)
	v_mfma_f32_16x16x32_bf16 v[94:97], v[130:133], v[146:149], v[94:97]
	v_mfma_f32_16x16x32_bf16 v[90:93], v[138:141], v[146:149], v[90:93]
	v_mfma_f32_16x16x32_bf16 v[86:89], v[130:133], v[154:157], v[86:89]
	v_mfma_f32_16x16x32_bf16 v[82:85], v[138:141], v[154:157], v[82:85]
	v_mfma_f32_16x16x32_bf16 v[78:81], v[130:133], v[162:165], v[78:81]
	v_mfma_f32_16x16x32_bf16 v[74:77], v[138:141], v[162:165], v[74:77]
	v_mfma_f32_16x16x32_bf16 v[70:73], v[130:133], v[170:173], v[70:73]
	v_mfma_f32_16x16x32_bf16 v[66:69], v[138:141], v[170:173], v[66:69]
	v_mfma_f32_16x16x32_bf16 v[94:97], v[134:137], v[150:153], v[94:97]
	v_mfma_f32_16x16x32_bf16 v[90:93], v[142:145], v[150:153], v[90:93]
	v_mfma_f32_16x16x32_bf16 v[86:89], v[134:137], v[158:161], v[86:89]
	v_mfma_f32_16x16x32_bf16 v[82:85], v[142:145], v[158:161], v[82:85]
	v_mfma_f32_16x16x32_bf16 v[78:81], v[134:137], v[166:169], v[78:81]
	v_mfma_f32_16x16x32_bf16 v[74:77], v[142:145], v[166:169], v[74:77]
	v_mfma_f32_16x16x32_bf16 v[70:73], v[134:137], v[174:177], v[70:73]
	v_mfma_f32_16x16x32_bf16 v[66:69], v[142:145], v[174:177], v[66:69]
	s_setprio 0
	s_mov_b32 m0, s61
	v_lshl_add_u64 v[220:221], s[38:39], 0, v[178:179]
	s_barrier
	ds_read_b128 v[170:173], v215 offset:49152
	ds_read_b128 v[174:177], v215 offset:50176
	ds_read_b128 v[162:165], v215 offset:51200
	ds_read_b128 v[166:169], v215 offset:52224
	ds_read_b128 v[154:157], v215 offset:53248
	ds_read_b128 v[158:161], v215 offset:54272
	ds_read_b128 v[146:149], v215 offset:55296
	ds_read_b128 v[150:153], v215 offset:56320
	global_load_lds_dwordx4 v[220:221], off
	v_lshl_add_u64 v[220:221], s[38:39], 0, v[182:183]
	s_mov_b32 m0, s58
	s_nop 0
	global_load_lds_dwordx4 v[220:221], off
	s_barrier
	s_waitcnt lgkmcnt(0)
	s_setprio 1
	s_waitcnt lgkmcnt(0)
	v_mfma_f32_16x16x32_bf16 v[62:65], v[196:199], v[170:173], v[62:65]
	v_mfma_f32_16x16x32_bf16 v[58:61], v[232:235], v[170:173], v[58:61]
	v_mfma_f32_16x16x32_bf16 v[54:57], v[196:199], v[162:165], v[54:57]
	v_mfma_f32_16x16x32_bf16 v[50:53], v[232:235], v[162:165], v[50:53]
	v_mfma_f32_16x16x32_bf16 v[46:49], v[196:199], v[154:157], v[46:49]
	v_mfma_f32_16x16x32_bf16 v[42:45], v[232:235], v[154:157], v[42:45]
	v_mfma_f32_16x16x32_bf16 v[38:41], v[196:199], v[146:149], v[38:41]
	v_mfma_f32_16x16x32_bf16 v[34:37], v[232:235], v[146:149], v[34:37]
	v_mfma_f32_16x16x32_bf16 v[62:65], v[216:219], v[174:177], v[62:65]
	v_mfma_f32_16x16x32_bf16 v[58:61], v[244:247], v[174:177], v[58:61]
	v_mfma_f32_16x16x32_bf16 v[54:57], v[216:219], v[166:169], v[54:57]
	v_mfma_f32_16x16x32_bf16 v[50:53], v[244:247], v[166:169], v[50:53]
	v_mfma_f32_16x16x32_bf16 v[46:49], v[216:219], v[158:161], v[46:49]
	v_mfma_f32_16x16x32_bf16 v[42:45], v[244:247], v[158:161], v[42:45]
	v_mfma_f32_16x16x32_bf16 v[38:41], v[216:219], v[150:153], v[38:41]
	v_mfma_f32_16x16x32_bf16 v[34:37], v[244:247], v[150:153], v[34:37]
	s_setprio 0
	s_barrier
	v_or_b32_e32 v0, s7, v202
	v_cmp_eq_u32_e64 s[38:39], 0, v0
	s_and_saveexec_b64 s[76:77], s[38:39]
	s_cbranch_execz .LBB0_919
	v_cmp_lt_i32_e32 vcc, 0x20f, v203
	v_add_u32_e32 v0, s90, v203
	s_and_saveexec_b64 s[78:79], vcc
	s_cbranch_execz .LBB0_918
	v_mov_b64_e32 v[196:197], s[40:41]
	flat_atomic_add v0, v[196:197], v224 sc0
	s_movk_i32 s0, 0x20f
	s_waitcnt vmcnt(0) lgkmcnt(0)
	v_cmp_lt_i32_e64 s[38:39], s0, v0
	v_add_u32_e32 v0, s63, v0
	s_and_saveexec_b64 s[0:1], s[38:39]
	s_cbranch_execz .LBB0_917
	v_mov_b64_e32 v[196:197], s[42:43]
	flat_atomic_add v0, v[196:197], v224 sc0
	s_movk_i32 s8, 0x20f
	s_waitcnt vmcnt(0) lgkmcnt(0)
	v_cmp_lt_i32_e64 s[38:39], s8, v0
	v_add_u32_e32 v0, s2, v0
	s_and_saveexec_b64 s[80:81], s[38:39]
	s_cbranch_execz .LBB0_916
	v_mov_b64_e32 v[196:197], s[44:45]
	flat_atomic_add v0, v[196:197], v224 sc0
	s_waitcnt vmcnt(0) lgkmcnt(0)
	v_cmp_lt_i32_e64 s[38:39], s8, v0
	v_add_u32_e32 v0, s3, v0
	s_and_saveexec_b64 s[82:83], s[38:39]
	s_cbranch_execz .LBB0_915
	v_mov_b64_e32 v[196:197], s[50:51]
	flat_atomic_add v0, v[196:197], v224 sc0
	s_waitcnt vmcnt(0) lgkmcnt(0)
	v_cmp_lt_i32_e64 s[38:39], s8, v0
	v_add_u32_e32 v0, s95, v0
	s_and_saveexec_b64 s[84:85], s[38:39]
	s_cbranch_execz .LBB0_914
	v_mov_b64_e32 v[196:197], s[54:55]
	flat_atomic_add v0, v[196:197], v224 sc0
	s_waitcnt vmcnt(0) lgkmcnt(0)
	v_cmp_lt_i32_e64 s[38:39], s8, v0
	v_add_u32_e32 v0, s28, v0
	s_and_saveexec_b64 s[86:87], s[38:39]
	s_cbranch_execz .LBB0_913
	v_readlane_b32 s8, v254, 54
	v_readlane_b32 s9, v254, 55
	s_nop 1
	v_mov_b64_e32 v[196:197], s[8:9]
	flat_atomic_add v0, v[196:197], v224 sc0
	s_movk_i32 s8, 0x20f
	s_waitcnt vmcnt(0) lgkmcnt(0)
	v_cmp_lt_i32_e64 s[38:39], s8, v0
	v_readlane_b32 s8, v254, 39
	s_nop 1
	v_add_u32_e32 v0, s8, v0
	s_and_saveexec_b64 s[88:89], s[38:39]
	s_cbranch_execz .LBB0_912
	v_readlane_b32 s8, v254, 56
	v_readlane_b32 s9, v254, 57
	s_nop 1
	v_mov_b64_e32 v[196:197], s[8:9]
	flat_atomic_add v0, v[196:197], v224 sc0
	v_readlane_b32 s8, v254, 43
	s_waitcnt vmcnt(0) lgkmcnt(0)
	v_cmp_gt_i32_e64 s[38:39], s91, v0
	v_add_u32_e32 v191, s8, v0
	s_nop 0
	v_cndmask_b32_e64 v0, -1, v191, s[38:39]
	s_branch .LBB0_912
